# prompt attention O epilogue: one reciprocal per row (rcp + 2 Newton steps) and 16 multiplies instead of 16 full divisions; lane-quad 4x4 transposes so each lane stores 4 columns with one 8-byte store
# speedup vs baseline: 1.0029x; 1.0022x over previous
.LBB0_2652:
	s_or_b64 exec, exec, s[22:23]
	ds_write_b64 v84, v[102:103] offset:288
	s_waitcnt lgkmcnt(0)
	s_barrier
	ds_read_b128 v[32:35], v85
	ds_read_b128 v[72:75], v85 offset:64
	s_waitcnt lgkmcnt(1)
	v_mfma_f32_16x16x32_bf16 v[32:35], v[28:31], v[32:35], 0
	v_ashrrev_i32_e32 v69, 31, v68
	s_cmp_lg_u32 s26, 0
	s_cselect_b64 s[34:35], -1, 0
	s_waitcnt lgkmcnt(0)
	v_mfma_f32_16x16x32_bf16 v[72:75], v[24:27], v[72:75], v[32:35]
	s_nop 2
	ds_read_b128 v[32:35], v85 offset:2304
	ds_read_b128 v[104:107], v85 offset:2368
	s_and_b64 s[24:25], s[34:35], s[4:5]
	s_or_b64 s[22:23], s[34:35], s[8:9]
	s_waitcnt lgkmcnt(1)
	v_mfma_f32_16x16x32_bf16 v[32:35], v[28:31], v[32:35], 0
	v_mul_f32_e32 v36, 0x3e000000, v72
	v_cndmask_b32_e64 v67, v96, v36, s[24:25]
	s_and_b64 s[26:27], s[34:35], s[6:7]
	s_waitcnt lgkmcnt(0)
	v_mfma_f32_16x16x32_bf16 v[104:107], v[24:27], v[104:107], v[32:35]
	s_nop 2
	ds_read_b128 v[32:35], v85 offset:4608
	ds_read_b128 v[108:111], v85 offset:4672
	v_mul_f32_e32 v74, 0x3e000000, v74
	s_and_b64 s[28:29], s[34:35], s[14:15]
	s_waitcnt lgkmcnt(1)
	v_mfma_f32_16x16x32_bf16 v[32:35], v[28:31], v[32:35], 0
	v_mul_f32_e32 v37, 0x3e000000, v104
	v_cndmask_b32_e64 v37, v96, v37, s[34:35]
	v_cndmask_b32_e64 v74, v96, v74, s[28:29]
	s_waitcnt lgkmcnt(0)
	v_mfma_f32_16x16x32_bf16 v[108:111], v[24:27], v[108:111], v[32:35]
	s_nop 2
	ds_read_b128 v[32:35], v85 offset:6912
	ds_read_b128 v[112:115], v85 offset:6976
	ds_read_b128 v[116:119], v85 offset:9216
	ds_read_b128 v[120:123], v85 offset:9280
	s_waitcnt lgkmcnt(3)
	v_mfma_f32_16x16x32_bf16 v[32:35], v[28:31], v[32:35], 0
	ds_read_b128 v[124:127], v85 offset:11584
	v_mul_f32_e32 v36, 0x3e000000, v108
	v_cndmask_b32_e64 v72, v96, v36, s[34:35]
	s_waitcnt lgkmcnt(3)
	v_mfma_f32_16x16x32_bf16 v[112:115], v[24:27], v[112:115], v[32:35]
	v_mul_f32_e32 v106, 0x3e000000, v106
	v_mul_f32_e32 v110, 0x3e000000, v110
	v_cndmask_b32_e64 v106, v96, v106, s[34:35]
	v_lshl_add_u64 v[32:33], v[68:69], 2, s[80:81]
	global_load_dword v35, v[32:33], off
	s_waitcnt lgkmcnt(2)
	v_mfma_f32_16x16x32_bf16 v[116:119], v[28:31], v[116:119], 0
	v_lshl_add_u64 v[32:33], v[70:71], 1, v[50:51]
	ds_read_b128 v[68:71], v85 offset:13824
	v_mul_f32_e32 v36, 0x3e000000, v112
	s_waitcnt lgkmcnt(2)
	v_mfma_f32_16x16x32_bf16 v[116:119], v[24:27], v[120:123], v[116:119]
	ds_read_b128 v[120:123], v85 offset:11520
	v_cndmask_b32_e64 v97, v96, v36, s[34:35]
	v_cndmask_b32_e64 v110, v96, v110, s[34:35]
	s_waitcnt lgkmcnt(0)
	v_mfma_f32_16x16x32_bf16 v[120:123], v[28:31], v[120:123], 0
	v_mul_f32_e32 v114, 0x3e000000, v114
	s_nop 1
	v_mul_f32_e32 v36, 0x3e000000, v116
	v_mul_f32_e32 v118, 0x3e000000, v118
	v_mfma_f32_16x16x32_bf16 v[120:123], v[24:27], v[124:127], v[120:123]
	ds_read_b128 v[124:127], v85 offset:13888
	ds_read_b128 v[128:131], v85 offset:16128
	ds_read_b128 v[132:135], v85 offset:16192
	ds_read_b128 v[136:139], v85 offset:18432
	ds_read_b128 v[140:143], v85 offset:18496
	v_cndmask_b32_e64 v114, v96, v114, s[34:35]
	v_mfma_f32_16x16x32_bf16 v[68:71], v[28:31], v[68:71], 0
	s_nop 0
	v_mul_f32_e32 v104, 0x3e000000, v120
	v_cndmask_b32_e64 v104, v96, v104, s[22:23]
	v_cndmask_b32_e64 v118, v96, v118, s[22:23]
	s_waitcnt lgkmcnt(4)
	v_mfma_f32_16x16x32_bf16 v[68:71], v[24:27], v[124:127], v[68:71]
	v_mul_f32_e32 v120, 0x3e000000, v122
	v_cndmask_b32_e64 v120, v96, v120, s[22:23]
	v_mul_f32_e32 v75, 0x3e000000, v75
	s_waitcnt lgkmcnt(3)
	v_mfma_f32_16x16x32_bf16 v[124:127], v[28:31], v[128:131], 0
	s_and_b64 s[30:31], s[34:35], s[18:19]
	s_nop 1
	v_mul_f32_e32 v68, 0x3e000000, v68
	v_cndmask_b32_e64 v68, v96, v68, s[22:23]
	s_waitcnt lgkmcnt(1)
	v_mfma_f32_16x16x32_bf16 v[28:31], v[28:31], v[136:139], 0
	v_mul_f32_e32 v69, 0x3e000000, v69
	v_cndmask_b32_e64 v69, v96, v69, s[22:23]
	v_mul_f32_e32 v70, 0x3e000000, v70
	v_mfma_f32_16x16x32_bf16 v[124:127], v[24:27], v[132:135], v[124:127]
	v_cndmask_b32_e64 v70, v96, v70, s[22:23]
	v_cndmask_b32_e64 v75, v96, v75, s[30:31]
	v_mul_f32_e32 v107, 0x3e000000, v107
	s_waitcnt lgkmcnt(0)
	v_mfma_f32_16x16x32_bf16 v[24:27], v[24:27], v[140:143], v[28:31]
	v_mul_f32_e32 v111, 0x3e000000, v111
	s_nop 1
	v_mul_f32_e32 v108, 0x3e000000, v124
	v_cndmask_b32_e64 v108, v96, v108, s[22:23]
	v_mul_f32_e32 v30, 0x3e000000, v109
	v_cndmask_b32_e64 v109, v96, v36, s[22:23]
	s_nop 0
	v_mul_f32_e32 v24, 0x3e000000, v24
	v_cndmask_b32_e64 v24, v24, v96, s[6:7]
	v_mul_f32_e32 v28, 0x3e000000, v73
	v_mul_f32_e32 v29, 0x3e000000, v105
	v_cndmask_b32_e64 v28, v96, v28, s[26:27]
	v_mul_f32_e32 v31, 0x3e000000, v113
	v_mul_f32_e32 v73, 0x3e000000, v117
	v_cndmask_b32_e64 v29, v96, v29, s[34:35]
	v_cndmask_b32_e64 v30, v96, v30, s[34:35]
	v_mul_f32_e32 v105, 0x3e000000, v121
	v_cndmask_b32_e64 v31, v96, v31, s[34:35]
	v_cndmask_b32_e64 v73, v96, v73, s[22:23]
	v_cndmask_b32_e64 v105, v96, v105, s[22:23]
	v_mul_f32_e32 v25, 0x3e000000, v25
	v_cndmask_b32_e64 v25, v25, v96, s[12:13]
	v_mul_f32_e32 v121, 0x3e000000, v126
	v_mul_f32_e32 v26, 0x3e000000, v26
	v_cndmask_b32_e64 v121, v96, v121, s[22:23]
	v_cndmask_b32_e64 v26, v26, v96, s[16:17]
	v_cndmask_b32_e64 v107, v96, v107, s[34:35]
	v_cndmask_b32_e64 v111, v96, v111, s[34:35]
	v_mul_f32_e32 v115, 0x3e000000, v115
	v_mul_f32_e32 v119, 0x3e000000, v119
	v_cndmask_b32_e64 v115, v96, v115, s[34:35]
	v_cndmask_b32_e64 v119, v96, v119, s[22:23]
	v_mul_f32_e32 v71, 0x3e000000, v71
	v_cndmask_b32_e64 v71, v96, v71, s[22:23]
	v_mul_f32_e32 v27, 0x3e000000, v27
	v_cndmask_b32_e64 v27, v27, v96, s[20:21]
	v_or_b32_e32 v34, s10, v48
	s_mul_i32 s10, s11, 0x880
	s_add_i32 s45, s45, s86
	s_cmpk_gt_i32 s45, 0x1ff
	s_waitcnt vmcnt(0)
	v_max_f32_e32 v36, v35, v35
	v_max_f32_e32 v112, v36, v67
	v_max3_f32 v112, v112, v37, v72
	v_max3_f32 v112, v112, v97, v109
	v_max3_f32 v112, v112, v104, v68
	v_max3_f32 v112, v112, v108, v24
	v_max_f32_e32 v113, v36, v28
	v_max3_f32 v113, v113, v29, v30
	v_mov_b32_dpp v116, v112 quad_perm:[1,0,3,2] row_mask:0xf bank_mask:0xf bound_ctrl:1
	v_max_f32_e32 v116, v116, v116
	v_max_f32_e32 v112, v112, v116
	v_max3_f32 v113, v113, v31, v73
	v_max3_f32 v113, v113, v105, v69
	v_mov_b32_dpp v116, v112 quad_perm:[2,3,0,1] row_mask:0xf bank_mask:0xf bound_ctrl:1
	v_max_f32_e32 v116, v116, v116
	v_max_f32_e32 v112, v112, v116
	s_nop 1
	v_mov_b32_dpp v116, v112 row_ror:4 row_mask:0xf bank_mask:0xf bound_ctrl:1
	v_max_f32_e32 v116, v116, v116
	v_max_f32_e32 v112, v112, v116
	s_nop 1
	v_mov_b32_dpp v116, v112 row_ror:8 row_mask:0xf bank_mask:0xf bound_ctrl:1
	v_max_f32_e32 v116, v116, v116
	v_max_f32_e32 v112, v112, v116
	v_mul_f32_e32 v116, 0x3e000000, v125
	v_cndmask_b32_e64 v116, v96, v116, s[22:23]
	v_max3_f32 v113, v113, v116, v25
	v_sub_f32_e32 v67, v67, v112
	v_mul_f32_e32 v67, 0x3fb8aa3b, v67
	v_mov_b32_dpp v117, v113 quad_perm:[1,0,3,2] row_mask:0xf bank_mask:0xf bound_ctrl:1
	v_max_f32_e32 v117, v117, v117
	v_max_f32_e32 v113, v113, v117
	v_exp_f32_e32 v67, v67
	v_sub_f32_e32 v37, v37, v112
	v_mov_b32_dpp v117, v113 quad_perm:[2,3,0,1] row_mask:0xf bank_mask:0xf bound_ctrl:1
	v_max_f32_e32 v117, v117, v117
	v_max_f32_e32 v113, v113, v117
	v_mul_f32_e32 v37, 0x3fb8aa3b, v37
	v_sub_f32_e32 v104, v104, v112
	v_mov_b32_dpp v117, v113 row_ror:4 row_mask:0xf bank_mask:0xf bound_ctrl:1
	v_max_f32_e32 v117, v117, v117
	v_max_f32_e32 v113, v113, v117
	v_mul_f32_e32 v104, 0x3fb8aa3b, v104
	v_exp_f32_e32 v104, v104
	v_mov_b32_dpp v117, v113 row_ror:8 row_mask:0xf bank_mask:0xf bound_ctrl:1
	v_max_f32_e32 v117, v117, v117
	v_max_f32_e32 v113, v113, v117
	v_max_f32_e32 v117, v36, v74
	v_max3_f32 v117, v117, v106, v110
	v_max3_f32 v117, v117, v114, v118
	v_max3_f32 v117, v117, v120, v70
	v_max3_f32 v117, v117, v121, v26
	v_sub_f32_e32 v28, v28, v113
	v_mul_f32_e32 v28, 0x3fb8aa3b, v28
	v_mov_b32_dpp v122, v117 quad_perm:[1,0,3,2] row_mask:0xf bank_mask:0xf bound_ctrl:1
	v_max_f32_e32 v122, v122, v122
	v_max_f32_e32 v117, v117, v122
	v_exp_f32_e32 v28, v28
	v_sub_f32_e32 v29, v29, v113
	v_mov_b32_dpp v122, v117 quad_perm:[2,3,0,1] row_mask:0xf bank_mask:0xf bound_ctrl:1
	v_max_f32_e32 v122, v122, v122
	v_max_f32_e32 v117, v117, v122
	v_mul_f32_e32 v29, 0x3fb8aa3b, v29
	v_exp_f32_e32 v29, v29
	v_mov_b32_dpp v122, v117 row_ror:4 row_mask:0xf bank_mask:0xf bound_ctrl:1
	v_max_f32_e32 v122, v122, v122
	v_max_f32_e32 v117, v117, v122
	v_sub_f32_e32 v30, v30, v113
	v_mul_f32_e32 v30, 0x3fb8aa3b, v30
	v_mov_b32_dpp v122, v117 row_ror:8 row_mask:0xf bank_mask:0xf bound_ctrl:1
	v_max_f32_e32 v122, v122, v122
	v_max_f32_e32 v136, v117, v122
	v_max_f32_e32 v117, v36, v75
	v_max3_f32 v117, v117, v107, v111
	v_mul_f32_e32 v122, 0x3e000000, v123
	v_max3_f32 v117, v117, v115, v119
	v_cndmask_b32_e64 v122, v96, v122, s[22:23]
	v_mul_f32_e32 v123, 0x3e000000, v127
	v_max3_f32 v117, v117, v122, v71
	v_cndmask_b32_e64 v123, v96, v123, s[22:23]
	v_max3_f32 v117, v117, v123, v27
	v_sub_f32_e32 v26, v26, v136
	v_mul_f32_e32 v26, 0x3fb8aa3b, v26
	v_mov_b32_dpp v124, v117 quad_perm:[1,0,3,2] row_mask:0xf bank_mask:0xf bound_ctrl:1
	v_max_f32_e32 v124, v124, v124
	v_max_f32_e32 v117, v117, v124
	v_exp_f32_e32 v141, v26
	v_sub_f32_e32 v74, v74, v136
	v_mov_b32_dpp v124, v117 quad_perm:[2,3,0,1] row_mask:0xf bank_mask:0xf bound_ctrl:1
	v_max_f32_e32 v124, v124, v124
	v_max_f32_e32 v117, v117, v124
	v_mul_f32_e32 v74, 0x3fb8aa3b, v74
	v_exp_f32_e32 v125, v74
	v_mov_b32_dpp v124, v117 row_ror:4 row_mask:0xf bank_mask:0xf bound_ctrl:1
	v_max_f32_e32 v124, v124, v124
	v_max_f32_e32 v117, v117, v124
	v_sub_f32_e32 v74, v106, v136
	v_mul_f32_e32 v74, 0x3fb8aa3b, v74
	v_mov_b32_dpp v124, v117 row_ror:8 row_mask:0xf bank_mask:0xf bound_ctrl:1
	v_max_f32_e32 v124, v124, v124
	v_max_f32_e32 v137, v117, v124
	v_sub_f32_e32 v26, v75, v137
	v_mul_f32_e32 v26, 0x3fb8aa3b, v26
	v_exp_f32_e32 v142, v26
	v_sub_f32_e32 v26, v107, v137
	v_mul_f32_e32 v26, 0x3fb8aa3b, v26
	v_exp_f32_e32 v143, v26
	v_sub_f32_e32 v26, v111, v137
	v_mul_f32_e32 v26, 0x3fb8aa3b, v26
	v_exp_f32_e32 v144, v26
	v_sub_f32_e32 v26, v115, v137
	v_mul_f32_e32 v26, 0x3fb8aa3b, v26
	v_exp_f32_e32 v145, v26
	v_sub_f32_e32 v26, v119, v137
	v_mul_f32_e32 v26, 0x3fb8aa3b, v26
	v_exp_f32_e32 v146, v26
	v_sub_f32_e32 v26, v122, v137
	v_mul_f32_e32 v26, 0x3fb8aa3b, v26
	v_exp_f32_e32 v147, v26
	v_sub_f32_e32 v26, v71, v137
	v_mul_f32_e32 v26, 0x3fb8aa3b, v26
	v_exp_f32_e32 v148, v26
	v_sub_f32_e32 v26, v123, v137
	v_mul_f32_e32 v26, 0x3fb8aa3b, v26
	v_exp_f32_e32 v149, v26
	v_sub_f32_e32 v26, v27, v137
	v_mul_f32_e32 v26, 0x3fb8aa3b, v26
	v_exp_f32_e32 v150, v26
	v_bfe_u32 v26, v67, 16, 1
	v_add3_u32 v26, v67, v26, s43
	ds_write_b16_d16_hi v86, v26
	v_bfe_u32 v26, v28, 16, 1
	v_add3_u32 v26, v28, v26, s43
	v_exp_f32_e32 v124, v37
	ds_write_b16_d16_hi v87, v26
	v_bfe_u32 v26, v125, 16, 1
	v_add3_u32 v26, v125, v26, s43
	ds_write_b16_d16_hi v87, v26 offset:336
	v_bfe_u32 v26, v142, 16, 1
	v_add3_u32 v26, v142, v26, s43
	v_exp_f32_e32 v132, v74
	ds_write_b16_d16_hi v87, v26 offset:672
	v_bfe_u32 v26, v124, 16, 1
	v_add3_u32 v26, v124, v26, s43
	v_sub_f32_e32 v37, v72, v112
	ds_write_b16_d16_hi v86, v26 offset:32
	v_bfe_u32 v26, v29, 16, 1
	v_mul_f32_e32 v37, 0x3fb8aa3b, v37
	v_add3_u32 v26, v29, v26, s43
	v_exp_f32_e32 v72, v37
	ds_write_b16_d16_hi v87, v26 offset:32
	v_bfe_u32 v26, v132, 16, 1
	v_add3_u32 v26, v132, v26, s43
	v_exp_f32_e32 v30, v30
	v_sub_f32_e32 v74, v110, v136
	ds_write_b16_d16_hi v87, v26 offset:368
	v_bfe_u32 v26, v143, 16, 1
	v_mul_f32_e32 v74, 0x3fb8aa3b, v74
	v_add3_u32 v26, v143, v26, s43
	v_exp_f32_e32 v133, v74
	ds_write_b16_d16_hi v87, v26 offset:704
	v_bfe_u32 v26, v72, 16, 1
	v_add3_u32 v26, v72, v26, s43
	v_sub_f32_e32 v37, v97, v112
	ds_write_b16_d16_hi v86, v26 offset:64
	v_bfe_u32 v26, v30, 16, 1
	v_mul_f32_e32 v37, 0x3fb8aa3b, v37
	v_add3_u32 v26, v30, v26, s43
	v_exp_f32_e32 v97, v37
	v_sub_f32_e32 v31, v31, v113
	ds_write_b16_d16_hi v87, v26 offset:64
	v_bfe_u32 v26, v133, 16, 1
	v_mul_f32_e32 v31, 0x3fb8aa3b, v31
	v_add3_u32 v26, v133, v26, s43
	v_exp_f32_e32 v31, v31
	v_sub_f32_e32 v74, v114, v136
	ds_write_b16_d16_hi v87, v26 offset:400
	v_bfe_u32 v26, v144, 16, 1
	v_mul_f32_e32 v74, 0x3fb8aa3b, v74
	v_add3_u32 v26, v144, v26, s43
	v_exp_f32_e32 v134, v74
	ds_write_b16_d16_hi v87, v26 offset:736
	v_bfe_u32 v26, v97, 16, 1
	v_add3_u32 v26, v97, v26, s43
	v_sub_f32_e32 v37, v109, v112
	ds_write_b16_d16_hi v86, v26 offset:96
	v_bfe_u32 v26, v31, 16, 1
	v_mul_f32_e32 v37, 0x3fb8aa3b, v37
	v_add3_u32 v26, v31, v26, s43
	v_exp_f32_e32 v109, v37
	v_sub_f32_e32 v73, v73, v113
	ds_write_b16_d16_hi v87, v26 offset:96
	v_bfe_u32 v26, v134, 16, 1
	v_mul_f32_e32 v73, 0x3fb8aa3b, v73
	v_add3_u32 v26, v134, v26, s43
	v_exp_f32_e32 v73, v73
	v_sub_f32_e32 v74, v118, v136
	ds_write_b16_d16_hi v87, v26 offset:432
	v_bfe_u32 v26, v145, 16, 1
	v_mul_f32_e32 v74, 0x3fb8aa3b, v74
	v_add3_u32 v26, v145, v26, s43
	v_exp_f32_e32 v135, v74
	ds_write_b16_d16_hi v87, v26 offset:768
	v_bfe_u32 v26, v109, 16, 1
	v_add3_u32 v26, v109, v26, s43
	ds_write_b16_d16_hi v86, v26 offset:128
	v_bfe_u32 v26, v73, 16, 1
	v_add3_u32 v26, v73, v26, s43
	v_sub_f32_e32 v105, v105, v113
	ds_write_b16_d16_hi v87, v26 offset:128
	v_bfe_u32 v26, v135, 16, 1
	v_mul_f32_e32 v105, 0x3fb8aa3b, v105
	v_add3_u32 v26, v135, v26, s43
	v_exp_f32_e32 v105, v105
	v_sub_f32_e32 v74, v120, v136
	ds_write_b16_d16_hi v87, v26 offset:464
	v_bfe_u32 v26, v146, 16, 1
	v_mul_f32_e32 v74, 0x3fb8aa3b, v74
	v_add3_u32 v26, v146, v26, s43
	v_exp_f32_e32 v138, v74
	ds_write_b16_d16_hi v87, v26 offset:800
	v_bfe_u32 v26, v104, 16, 1
	v_add3_u32 v26, v104, v26, s43
	v_sub_f32_e32 v68, v68, v112
	ds_write_b16_d16_hi v86, v26 offset:160
	v_bfe_u32 v26, v105, 16, 1
	v_mul_f32_e32 v68, 0x3fb8aa3b, v68
	v_add3_u32 v26, v105, v26, s43
	v_exp_f32_e32 v68, v68
	v_sub_f32_e32 v69, v69, v113
	ds_write_b16_d16_hi v87, v26 offset:160
	v_bfe_u32 v26, v138, 16, 1
	v_mul_f32_e32 v69, 0x3fb8aa3b, v69
	v_add3_u32 v26, v138, v26, s43
	v_exp_f32_e32 v69, v69
	v_sub_f32_e32 v70, v70, v136
	ds_write_b16_d16_hi v87, v26 offset:496
	v_bfe_u32 v26, v147, 16, 1
	v_mul_f32_e32 v70, 0x3fb8aa3b, v70
	v_add3_u32 v26, v147, v26, s43
	v_exp_f32_e32 v139, v70
	ds_write_b16_d16_hi v87, v26 offset:832
	v_bfe_u32 v26, v68, 16, 1
	v_add3_u32 v26, v68, v26, s43
	v_sub_f32_e32 v108, v108, v112
	ds_write_b16_d16_hi v86, v26 offset:192
	v_bfe_u32 v26, v69, 16, 1
	v_add_f32_e32 v117, 0, v67
	v_mul_f32_e32 v108, 0x3fb8aa3b, v108
	v_add3_u32 v26, v69, v26, s43
	v_add_f32_e32 v37, v124, v117
	v_exp_f32_e32 v108, v108
	v_sub_f32_e32 v116, v116, v113
	ds_write_b16_d16_hi v87, v26 offset:192
	v_bfe_u32 v26, v139, 16, 1
	v_add_f32_e32 v37, v72, v37
	v_sub_f32_e32 v24, v24, v112
	v_mul_f32_e32 v116, 0x3fb8aa3b, v116
	v_add3_u32 v26, v139, v26, s43
	v_add_f32_e32 v37, v97, v37
	v_mul_f32_e32 v24, 0x3fb8aa3b, v24
	v_exp_f32_e32 v116, v116
	v_sub_f32_e32 v70, v121, v136
	ds_write_b16_d16_hi v87, v26 offset:528
	v_bfe_u32 v26, v148, 16, 1
	v_add_f32_e32 v37, v109, v37
	v_exp_f32_e32 v24, v24
	v_mul_f32_e32 v70, 0x3fb8aa3b, v70
	v_add3_u32 v26, v148, v26, s43
	v_add_f32_e32 v37, v104, v37
	v_exp_f32_e32 v140, v70
	ds_write_b16_d16_hi v87, v26 offset:864
	v_bfe_u32 v26, v108, 16, 1
	v_add_f32_e32 v37, v68, v37
	v_add3_u32 v26, v108, v26, s43
	v_add_f32_e32 v37, v108, v37
	v_sub_f32_e32 v112, v35, v112
	ds_write_b16_d16_hi v86, v26 offset:224
	v_bfe_u32 v26, v116, 16, 1
	v_add_f32_e32 v37, v24, v37
	v_mul_f32_e32 v112, 0x3fb8aa3b, v112
	v_add3_u32 v26, v116, v26, s43
	v_add_f32_dpp v37, v37, v37 quad_perm:[1,0,3,2] row_mask:0xf bank_mask:0xf bound_ctrl:1
	v_exp_f32_e32 v112, v112
	v_sub_f32_e32 v25, v25, v113
	ds_write_b16_d16_hi v87, v26 offset:224
	v_bfe_u32 v26, v140, 16, 1
	v_add_f32_dpp v37, v37, v37 quad_perm:[2,3,0,1] row_mask:0xf bank_mask:0xf bound_ctrl:1
	v_mul_f32_e32 v25, 0x3fb8aa3b, v25
	v_add3_u32 v26, v140, v26, s43
	v_add_f32_dpp v37, v37, v37 row_ror:4 row_mask:0xf bank_mask:0xf bound_ctrl:1
	v_exp_f32_e32 v25, v25
	ds_write_b16_d16_hi v87, v26 offset:560
	v_bfe_u32 v26, v149, 16, 1
	v_add_f32_dpp v37, v37, v37 row_ror:8 row_mask:0xf bank_mask:0xf bound_ctrl:1
	v_add3_u32 v26, v149, v26, s43
	v_add_f32_e32 v37, v112, v37
	v_add_f32_e32 v112, 0, v28
	ds_write_b16_d16_hi v87, v26 offset:896
	v_bfe_u32 v26, v24, 16, 1
	v_add_f32_e32 v112, v29, v112
	v_add3_u32 v24, v24, v26, s43
	v_add_f32_e32 v112, v30, v112
	ds_write_b16_d16_hi v86, v24 offset:256
	v_bfe_u32 v24, v25, 16, 1
	v_add_f32_e32 v112, v31, v112
	v_add3_u32 v24, v25, v24, s43
	v_add_f32_e32 v112, v73, v112
	ds_write_b16_d16_hi v87, v24 offset:256
	v_bfe_u32 v24, v141, 16, 1
	v_add_f32_e32 v112, v105, v112
	v_add3_u32 v24, v141, v24, s43
	v_add_f32_e32 v112, v69, v112
	ds_write_b16_d16_hi v87, v24 offset:592
	v_bfe_u32 v24, v150, 16, 1
	v_add_f32_e32 v112, v116, v112
	v_add3_u32 v24, v150, v24, s43
	v_add_f32_e32 v112, v25, v112
	ds_write_b16_d16_hi v87, v24 offset:928
	ds_read_b128 v[24:27], v88
	v_add_f32_dpp v112, v112, v112 quad_perm:[1,0,3,2] row_mask:0xf bank_mask:0xf bound_ctrl:1
	v_sub_f32_e32 v68, v35, v113
	v_mul_f32_e32 v97, 0x3fb8aa3b, v68
	v_add_f32_dpp v112, v112, v112 quad_perm:[2,3,0,1] row_mask:0xf bank_mask:0xf bound_ctrl:1
	v_exp_f32_e32 v97, v97
	s_nop 0
	v_add_f32_dpp v28, v112, v112 row_ror:4 row_mask:0xf bank_mask:0xf bound_ctrl:1
	s_nop 1
	v_add_f32_dpp v67, v28, v28 row_ror:8 row_mask:0xf bank_mask:0xf bound_ctrl:1
	ds_read_b128 v[28:31], v89 offset:36864
	ds_read_b128 v[68:71], v89 offset:45824
	ds_read_b128 v[72:75], v88 offset:64
	ds_read_b128 v[104:107], v88 offset:256
	s_waitcnt lgkmcnt(3)
	v_mfma_f32_16x16x32_bf16 v[28:31], v[24:27], v[28:31], 0
	ds_read_b128 v[108:111], v89 offset:54784
	ds_read_b128 v[112:115], v89 offset:45888
	v_add_f32_e32 v67, v97, v67
	ds_read_b128 v[116:119], v89 offset:63744
	ds_read_b128 v[120:123], v89 offset:46080
	v_add_f32_e32 v97, 0, v125
	ds_read_b128 v[124:127], v89 offset:36928
	ds_read_b128 v[128:131], v89 offset:63808
	s_waitcnt lgkmcnt(8)
	v_mfma_f32_16x16x32_bf16 v[68:71], v[24:27], v[68:71], 0
	v_add_f32_e32 v97, v132, v97
	v_add_f32_e32 v97, v133, v97
	v_add_f32_e32 v97, v134, v97
	s_waitcnt lgkmcnt(5)
	v_mfma_f32_16x16x32_bf16 v[108:111], v[24:27], v[108:111], 0
	v_add_f32_e32 v97, v135, v97
	v_add_f32_e32 v97, v138, v97
	v_add_f32_e32 v97, v139, v97
	s_waitcnt lgkmcnt(3)
	v_mfma_f32_16x16x32_bf16 v[24:27], v[24:27], v[116:119], 0
	ds_read_b128 v[116:119], v89 offset:36992
	v_add_f32_e32 v97, v140, v97
	v_add_f32_e32 v97, v141, v97
	s_waitcnt lgkmcnt(2)
	v_mfma_f32_16x16x32_bf16 v[28:31], v[72:75], v[124:127], v[28:31]
	ds_read_b128 v[124:127], v89 offset:54848
	v_add_f32_dpp v97, v97, v97 quad_perm:[1,0,3,2] row_mask:0xf bank_mask:0xf bound_ctrl:1
	v_mfma_f32_16x16x32_bf16 v[68:71], v[72:75], v[112:115], v[68:71]
	ds_read_b128 v[112:115], v88 offset:128
	ds_read_b128 v[132:135], v89 offset:54912
	v_add_f32_dpp v97, v97, v97 quad_perm:[2,3,0,1] row_mask:0xf bank_mask:0xf bound_ctrl:1
	s_waitcnt lgkmcnt(2)
	v_mfma_f32_16x16x32_bf16 v[108:111], v[72:75], v[124:127], v[108:111]
	v_add_f32_dpp v97, v97, v97 row_ror:4 row_mask:0xf bank_mask:0xf bound_ctrl:1
	v_mfma_f32_16x16x32_bf16 v[24:27], v[72:75], v[128:131], v[24:27]
	ds_read_b128 v[72:75], v89 offset:45952
	ds_read_b128 v[124:127], v88 offset:192
	s_waitcnt lgkmcnt(1)
	v_mfma_f32_16x16x32_bf16 v[68:71], v[112:115], v[72:75], v[68:71]
	v_sub_f32_e32 v72, v35, v136
	v_mul_f32_e32 v128, 0x3fb8aa3b, v72
	ds_read_b128 v[72:75], v89 offset:63872
	v_mfma_f32_16x16x32_bf16 v[28:31], v[112:115], v[116:119], v[28:31]
	ds_read_b128 v[116:119], v89 offset:46016
	v_exp_f32_e32 v136, v128
	v_mfma_f32_16x16x32_bf16 v[108:111], v[112:115], v[132:135], v[108:111]
	ds_read_b128 v[128:131], v89 offset:37056
	ds_read_b128 v[132:135], v89 offset:63936
	s_waitcnt lgkmcnt(3)
	v_mfma_f32_16x16x32_bf16 v[24:27], v[112:115], v[72:75], v[24:27]
	v_add_f32_dpp v72, v97, v97 row_ror:8 row_mask:0xf bank_mask:0xf bound_ctrl:1
	v_add_f32_e32 v112, 0, v142
	v_add_f32_e32 v97, v136, v72
	ds_read_b128 v[72:75], v89 offset:37120
	s_waitcnt lgkmcnt(2)
	v_mfma_f32_16x16x32_bf16 v[28:31], v[124:127], v[128:131], v[28:31]
	v_add_f32_e32 v128, v143, v112
	ds_read_b128 v[112:115], v89 offset:54976
	v_mfma_f32_16x16x32_bf16 v[68:71], v[124:127], v[116:119], v[68:71]
	v_add_f32_e32 v116, v144, v128
	v_add_f32_e32 v128, v145, v116
	ds_read_b128 v[116:119], v89 offset:55040
	s_waitcnt lgkmcnt(1)
	v_mfma_f32_16x16x32_bf16 v[108:111], v[124:127], v[112:115], v[108:111]
	v_add_f32_e32 v112, v146, v128
	v_add_f32_e32 v112, v147, v112
	v_add_f32_e32 v112, v148, v112
	v_add_f32_e32 v112, v149, v112
	v_add_f32_e32 v112, v150, v112
	v_mfma_f32_16x16x32_bf16 v[72:75], v[104:107], v[72:75], v[28:31]
	s_nop 0
	v_add_f32_dpp v112, v112, v112 quad_perm:[1,0,3,2] row_mask:0xf bank_mask:0xf bound_ctrl:1
	v_mfma_f32_16x16x32_bf16 v[24:27], v[124:127], v[132:135], v[24:27]
	s_nop 0
	v_add_f32_dpp v28, v112, v112 quad_perm:[2,3,0,1] row_mask:0xf bank_mask:0xf bound_ctrl:1
	s_nop 2
	v_add_f32_dpp v28, v28, v28 row_ror:4 row_mask:0xf bank_mask:0xf bound_ctrl:1
	v_mfma_f32_16x16x32_bf16 v[68:71], v[104:107], v[120:123], v[68:71]
	v_add_f32_dpp v112, v28, v28 row_ror:8 row_mask:0xf bank_mask:0xf bound_ctrl:1
	v_sub_f32_e32 v28, v35, v137
	v_mul_f32_e32 v28, 0x3fb8aa3b, v28
	v_exp_f32_e32 v113, v28
	ds_read_b128 v[28:31], v89 offset:64000
	s_waitcnt lgkmcnt(0)
	v_mfma_f32_16x16x32_bf16 v[24:27], v[104:107], v[28:31], v[24:27]
	v_or_b32_e32 v28, v34, v42
	v_mad_u64_u32 v[28:29], s[52:53], v28, s44, v[32:33]
	v_add_u32_e32 v29, s10, v29
	v_mfma_f32_16x16x32_bf16 v[108:111], v[104:107], v[116:119], v[108:111]
	v_add_f32_e32 v112, v113, v112
	v_add_co_u32_e32 v30, vcc, 0x1000, v28
	s_nop 1
	v_addc_co_u32_e32 v31, vcc, 0, v29, vcc
	v_rcp_f32_e32 v194, v37
	v_rcp_f32_e32 v195, v67
	v_rcp_f32_e32 v196, v97
	v_rcp_f32_e32 v197, v112
	s_nop 0
	v_fma_f32 v240, -v37, v194, 1.0
	v_fma_f32 v241, -v67, v195, 1.0
	v_fma_f32 v242, -v97, v196, 1.0
	v_fma_f32 v243, -v112, v197, 1.0
	v_fmac_f32_e32 v194, v240, v194
	v_fmac_f32_e32 v195, v241, v195
	v_fmac_f32_e32 v196, v242, v196
	v_fmac_f32_e32 v197, v243, v197
	v_fma_f32 v240, -v37, v194, 1.0
	v_fma_f32 v241, -v67, v195, 1.0
	v_fma_f32 v242, -v97, v196, 1.0
	v_fma_f32 v243, -v112, v197, 1.0
	v_fmac_f32_e32 v194, v240, v194
	v_fmac_f32_e32 v195, v241, v195
	v_fmac_f32_e32 v196, v242, v196
	v_fmac_f32_e32 v197, v243, v197
	v_mul_f32_e32 v198, v72, v194
	v_mul_f32_e32 v199, v73, v195
	v_mul_f32_e32 v200, v74, v196
	v_mul_f32_e32 v201, v75, v197
	v_mul_f32_e32 v202, v68, v194
	v_mul_f32_e32 v203, v69, v195
	v_mul_f32_e32 v204, v70, v196
	v_mul_f32_e32 v205, v71, v197
	v_mul_f32_e32 v206, v108, v194
	v_mul_f32_e32 v207, v109, v195
	v_mul_f32_e32 v208, v110, v196
	v_mul_f32_e32 v209, v111, v197
	v_mul_f32_e32 v210, v24, v194
	v_mul_f32_e32 v211, v25, v195
	v_mul_f32_e32 v212, v26, v196
	v_mul_f32_e32 v213, v27, v197
	v_and_b32_e32 v240, 3, v174
	v_mul_u32_u24_e32 v240, 0x87e, v240
	v_mov_b32_e32 v241, 0
	v_lshl_add_u64 v[238:239], v[28:29], 0, v[240:241]
	s_mov_b32 vcc_lo, 0x55555555
	s_mov_b32 vcc_hi, 0x55555555
	s_nop 1
	v_cndmask_b32_dpp v214, v199, v198, vcc quad_perm:[1,0,3,2] row_mask:0xf bank_mask:0xf
	v_cndmask_b32_dpp v216, v201, v200, vcc quad_perm:[1,0,3,2] row_mask:0xf bank_mask:0xf
	v_cndmask_b32_dpp v218, v203, v202, vcc quad_perm:[1,0,3,2] row_mask:0xf bank_mask:0xf
	v_cndmask_b32_dpp v220, v205, v204, vcc quad_perm:[1,0,3,2] row_mask:0xf bank_mask:0xf
	v_cndmask_b32_dpp v222, v207, v206, vcc quad_perm:[1,0,3,2] row_mask:0xf bank_mask:0xf
	v_cndmask_b32_dpp v224, v209, v208, vcc quad_perm:[1,0,3,2] row_mask:0xf bank_mask:0xf
	v_cndmask_b32_dpp v226, v211, v210, vcc quad_perm:[1,0,3,2] row_mask:0xf bank_mask:0xf
	v_cndmask_b32_dpp v228, v213, v212, vcc quad_perm:[1,0,3,2] row_mask:0xf bank_mask:0xf
	s_mov_b32 vcc_lo, 0xaaaaaaaa
	s_mov_b32 vcc_hi, 0xaaaaaaaa
	s_nop 1
	v_cndmask_b32_dpp v215, v198, v199, vcc quad_perm:[1,0,3,2] row_mask:0xf bank_mask:0xf
	v_cndmask_b32_dpp v217, v200, v201, vcc quad_perm:[1,0,3,2] row_mask:0xf bank_mask:0xf
	v_cndmask_b32_dpp v219, v202, v203, vcc quad_perm:[1,0,3,2] row_mask:0xf bank_mask:0xf
	v_cndmask_b32_dpp v221, v204, v205, vcc quad_perm:[1,0,3,2] row_mask:0xf bank_mask:0xf
	v_cndmask_b32_dpp v223, v206, v207, vcc quad_perm:[1,0,3,2] row_mask:0xf bank_mask:0xf
	v_cndmask_b32_dpp v225, v208, v209, vcc quad_perm:[1,0,3,2] row_mask:0xf bank_mask:0xf
	v_cndmask_b32_dpp v227, v210, v211, vcc quad_perm:[1,0,3,2] row_mask:0xf bank_mask:0xf
	v_cndmask_b32_dpp v229, v212, v213, vcc quad_perm:[1,0,3,2] row_mask:0xf bank_mask:0xf
	s_mov_b32 vcc_lo, 0x33333333
	s_mov_b32 vcc_hi, 0x33333333
	s_nop 1
	v_cndmask_b32_dpp v198, v216, v214, vcc quad_perm:[2,3,0,1] row_mask:0xf bank_mask:0xf
	v_cndmask_b32_dpp v199, v217, v215, vcc quad_perm:[2,3,0,1] row_mask:0xf bank_mask:0xf
	v_cndmask_b32_dpp v202, v220, v218, vcc quad_perm:[2,3,0,1] row_mask:0xf bank_mask:0xf
	v_cndmask_b32_dpp v203, v221, v219, vcc quad_perm:[2,3,0,1] row_mask:0xf bank_mask:0xf
	v_cndmask_b32_dpp v206, v224, v222, vcc quad_perm:[2,3,0,1] row_mask:0xf bank_mask:0xf
	v_cndmask_b32_dpp v207, v225, v223, vcc quad_perm:[2,3,0,1] row_mask:0xf bank_mask:0xf
	v_cndmask_b32_dpp v210, v228, v226, vcc quad_perm:[2,3,0,1] row_mask:0xf bank_mask:0xf
	v_cndmask_b32_dpp v211, v229, v227, vcc quad_perm:[2,3,0,1] row_mask:0xf bank_mask:0xf
	s_mov_b32 vcc_lo, 0xcccccccc
	s_mov_b32 vcc_hi, 0xcccccccc
	s_nop 1
	v_cndmask_b32_dpp v200, v214, v216, vcc quad_perm:[2,3,0,1] row_mask:0xf bank_mask:0xf
	v_cndmask_b32_dpp v201, v215, v217, vcc quad_perm:[2,3,0,1] row_mask:0xf bank_mask:0xf
	v_cndmask_b32_dpp v204, v218, v220, vcc quad_perm:[2,3,0,1] row_mask:0xf bank_mask:0xf
	v_cndmask_b32_dpp v205, v219, v221, vcc quad_perm:[2,3,0,1] row_mask:0xf bank_mask:0xf
	v_cndmask_b32_dpp v208, v222, v224, vcc quad_perm:[2,3,0,1] row_mask:0xf bank_mask:0xf
	v_cndmask_b32_dpp v209, v223, v225, vcc quad_perm:[2,3,0,1] row_mask:0xf bank_mask:0xf
	v_cndmask_b32_dpp v212, v226, v228, vcc quad_perm:[2,3,0,1] row_mask:0xf bank_mask:0xf
	v_cndmask_b32_dpp v213, v227, v229, vcc quad_perm:[2,3,0,1] row_mask:0xf bank_mask:0xf
	v_cvt_pk_bf16_f32 v230, v198, v199
	v_cvt_pk_bf16_f32 v231, v200, v201
	v_cvt_pk_bf16_f32 v232, v202, v203
	v_cvt_pk_bf16_f32 v233, v204, v205
	v_cvt_pk_bf16_f32 v234, v206, v207
	v_cvt_pk_bf16_f32 v235, v208, v209
	v_cvt_pk_bf16_f32 v236, v210, v211
	v_cvt_pk_bf16_f32 v237, v212, v213
	global_store_dwordx2 v[238:239], v[230:231], off offset:0
	global_store_dwordx2 v[238:239], v[232:233], off offset:32
	global_store_dwordx2 v[238:239], v[234:235], off offset:64
	global_store_dwordx2 v[238:239], v[236:237], off offset:96
	ds_read_b128 v[24:27], v90
	ds_read_b128 v[28:31], v90 offset:64
	s_waitcnt lgkmcnt(1)
	v_mfma_f32_16x16x32_bf16 v[24:27], v[16:19], v[24:27], 0
	s_waitcnt lgkmcnt(0)
	v_mfma_f32_16x16x32_bf16 v[28:31], v[20:23], v[28:31], v[24:27]
	s_nop 5
	ds_read_b128 v[24:27], v90 offset:2304
	ds_read_b128 v[68:71], v90 offset:2368
	v_mul_f32_e32 v29, 0x3e000000, v29
	s_waitcnt lgkmcnt(1)
	v_mfma_f32_16x16x32_bf16 v[24:27], v[16:19], v[24:27], 0
	v_cndmask_b32_e64 v29, v96, v29, s[26:27]
	v_mul_f32_e32 v30, 0x3e000000, v30
	v_cndmask_b32_e64 v30, v96, v30, s[28:29]
	s_waitcnt lgkmcnt(0)
	v_mfma_f32_16x16x32_bf16 v[68:71], v[20:23], v[68:71], v[24:27]
	s_nop 2
	ds_read_b128 v[24:27], v90 offset:4608
	ds_read_b128 v[72:75], v90 offset:4672
	v_mul_f32_e32 v31, 0x3e000000, v31
	v_cndmask_b32_e64 v31, v96, v31, s[30:31]
	s_waitcnt lgkmcnt(1)
	v_mfma_f32_16x16x32_bf16 v[24:27], v[16:19], v[24:27], 0
	v_mul_f32_e32 v69, 0x3e000000, v69
	v_cndmask_b32_e64 v69, v96, v69, s[34:35]
	v_mul_f32_e32 v70, 0x3e000000, v70
	s_waitcnt lgkmcnt(0)
	v_mfma_f32_16x16x32_bf16 v[72:75], v[20:23], v[72:75], v[24:27]
	s_nop 2
	ds_read_b128 v[24:27], v90 offset:6912
	ds_read_b128 v[104:107], v90 offset:6976
	v_cndmask_b32_e64 v70, v96, v70, s[34:35]
	v_mul_f32_e32 v71, 0x3e000000, v71
	s_waitcnt lgkmcnt(1)
	v_mfma_f32_16x16x32_bf16 v[24:27], v[16:19], v[24:27], 0
	v_mul_f32_e32 v73, 0x3e000000, v73
	v_cndmask_b32_e64 v73, v96, v73, s[34:35]
	v_mul_f32_e32 v74, 0x3e000000, v74
	s_waitcnt lgkmcnt(0)
	v_mfma_f32_16x16x32_bf16 v[104:107], v[20:23], v[104:107], v[24:27]
	s_nop 2
	ds_read_b128 v[24:27], v90 offset:9216
	ds_read_b128 v[108:111], v90 offset:9280
	v_cndmask_b32_e64 v74, v96, v74, s[34:35]
	v_mul_f32_e32 v75, 0x3e000000, v75
	s_waitcnt lgkmcnt(1)
	v_mfma_f32_16x16x32_bf16 v[24:27], v[16:19], v[24:27], 0
	v_mul_f32_e32 v97, 0x3e000000, v105
	v_cndmask_b32_e64 v97, v96, v97, s[22:23]
	v_mul_f32_e32 v106, 0x3e000000, v106
	s_waitcnt lgkmcnt(0)
	v_mfma_f32_16x16x32_bf16 v[108:111], v[20:23], v[108:111], v[24:27]
	s_nop 2
	ds_read_b128 v[24:27], v90 offset:11520
	ds_read_b128 v[112:115], v90 offset:11584
	v_cndmask_b32_e64 v106, v96, v106, s[22:23]
	v_cndmask_b32_e64 v71, v96, v71, s[34:35]
	s_waitcnt lgkmcnt(1)
	v_mfma_f32_16x16x32_bf16 v[24:27], v[16:19], v[24:27], 0
	v_mul_f32_e32 v37, 0x3e000000, v108
	v_cndmask_b32_e64 v37, v96, v37, s[22:23]
	v_mul_f32_e32 v110, 0x3e000000, v110
	s_waitcnt lgkmcnt(0)
	v_mfma_f32_16x16x32_bf16 v[112:115], v[20:23], v[112:115], v[24:27]
	s_nop 2
	ds_read_b128 v[24:27], v90 offset:13824
	ds_read_b128 v[116:119], v90 offset:13888
	v_cndmask_b32_e64 v110, v96, v110, s[22:23]
	v_cndmask_b32_e64 v75, v96, v75, s[34:35]
	s_waitcnt lgkmcnt(1)
	v_mfma_f32_16x16x32_bf16 v[24:27], v[16:19], v[24:27], 0
	v_mul_f32_e32 v67, 0x3e000000, v112
	v_cndmask_b32_e64 v67, v96, v67, s[22:23]
	v_mul_f32_e32 v105, 0x3e000000, v113
	s_waitcnt lgkmcnt(0)
	v_mfma_f32_16x16x32_bf16 v[116:119], v[20:23], v[116:119], v[24:27]
	s_nop 2
	ds_read_b128 v[24:27], v90 offset:16128
	ds_read_b128 v[120:123], v90 offset:16192
	v_cndmask_b32_e64 v105, v96, v105, s[22:23]
	v_mul_f32_e32 v112, 0x3e000000, v114
	s_waitcnt lgkmcnt(1)
	v_mfma_f32_16x16x32_bf16 v[24:27], v[16:19], v[24:27], 0
	v_mul_f32_e32 v108, 0x3e000000, v117
	v_cndmask_b32_e64 v108, v96, v108, s[22:23]
	v_mul_f32_e32 v113, 0x3e000000, v118
	s_waitcnt lgkmcnt(0)
	v_mfma_f32_16x16x32_bf16 v[24:27], v[20:23], v[120:123], v[24:27]
	ds_read_b128 v[120:123], v90 offset:18432
	ds_read_b128 v[124:127], v90 offset:18496
	v_cndmask_b32_e64 v112, v96, v112, s[22:23]
	v_cndmask_b32_e64 v113, v96, v113, s[22:23]
	s_waitcnt lgkmcnt(1)
	v_mfma_f32_16x16x32_bf16 v[16:19], v[16:19], v[120:123], 0
	s_nop 1
	v_mul_f32_e32 v114, 0x3e000000, v26
	v_mul_f32_e32 v107, 0x3e000000, v107
	v_mul_f32_e32 v111, 0x3e000000, v111
	s_waitcnt lgkmcnt(0)
	v_mfma_f32_16x16x32_bf16 v[16:19], v[20:23], v[124:127], v[16:19]
	v_mul_f32_e32 v20, 0x3e000000, v28
	v_cndmask_b32_e64 v20, v96, v20, s[24:25]
	v_mul_f32_e32 v22, 0x3e000000, v68
	v_mul_f32_e32 v23, 0x3e000000, v72
	v_max_f32_e32 v21, v36, v20
	v_cndmask_b32_e64 v22, v96, v22, s[34:35]
	v_cndmask_b32_e64 v23, v96, v23, s[34:35]
	v_mul_f32_e32 v28, 0x3e000000, v104
	v_max3_f32 v21, v21, v22, v23
	v_cndmask_b32_e64 v28, v96, v28, s[22:23]
	v_mul_f32_e32 v68, 0x3e000000, v116
	v_max3_f32 v21, v21, v28, v37
	v_cndmask_b32_e64 v68, v96, v68, s[22:23]
	v_mul_f32_e32 v16, 0x3e000000, v16
	v_max3_f32 v21, v21, v67, v68
	v_mul_f32_e32 v72, 0x3e000000, v24
	v_cndmask_b32_e64 v16, v16, v96, s[6:7]
	v_max3_f32 v21, v21, v72, v16
	v_mul_f32_e32 v104, 0x3e000000, v109
	v_cndmask_b32_e64 v104, v96, v104, s[22:23]
	v_mov_b32_dpp v72, v21 quad_perm:[1,0,3,2] row_mask:0xf bank_mask:0xf bound_ctrl:1
	v_max_f32_e32 v72, v72, v72
	v_max_f32_e32 v21, v21, v72
	v_mul_f32_e32 v17, 0x3e000000, v17
	v_mul_f32_e32 v109, 0x3e000000, v25
	v_mov_b32_dpp v72, v21 quad_perm:[2,3,0,1] row_mask:0xf bank_mask:0xf bound_ctrl:1
	v_max_f32_e32 v72, v72, v72
	v_max_f32_e32 v21, v21, v72
	v_cndmask_b32_e64 v17, v17, v96, s[12:13]
	v_mul_f32_e32 v18, 0x3e000000, v18
	v_mov_b32_dpp v72, v21 row_ror:4 row_mask:0xf bank_mask:0xf bound_ctrl:1
	v_max_f32_e32 v72, v72, v72
	v_max_f32_e32 v21, v21, v72
	v_cndmask_b32_e64 v18, v18, v96, s[16:17]
	v_cndmask_b32_e64 v107, v96, v107, s[22:23]
	v_mov_b32_dpp v72, v21 row_ror:8 row_mask:0xf bank_mask:0xf bound_ctrl:1
	v_max_f32_e32 v72, v72, v72
	v_max_f32_e32 v21, v21, v72
	v_max_f32_e32 v72, v36, v29
	v_max3_f32 v72, v72, v69, v73
	v_max3_f32 v72, v72, v97, v104
	v_max3_f32 v72, v72, v105, v108
	v_max3_f32 v72, v72, v109, v17
	v_cndmask_b32_e64 v111, v96, v111, s[22:23]
	v_mul_f32_e32 v19, 0x3e000000, v19
	v_mov_b32_dpp v109, v72 quad_perm:[1,0,3,2] row_mask:0xf bank_mask:0xf bound_ctrl:1
	v_max_f32_e32 v109, v109, v109
	v_max_f32_e32 v72, v72, v109
	v_mul_f32_e32 v116, 0x3e000000, v27
	v_cndmask_b32_e64 v19, v19, v96, s[20:21]
	v_mov_b32_dpp v109, v72 quad_perm:[2,3,0,1] row_mask:0xf bank_mask:0xf bound_ctrl:1
	v_max_f32_e32 v109, v109, v109
	v_max_f32_e32 v72, v72, v109
	v_sub_f32_e32 v20, v20, v21
	v_mul_f32_e32 v20, 0x3fb8aa3b, v20
	v_mov_b32_dpp v109, v72 row_ror:4 row_mask:0xf bank_mask:0xf bound_ctrl:1
	v_max_f32_e32 v109, v109, v109
	v_max_f32_e32 v72, v72, v109
	v_exp_f32_e32 v20, v20
	v_sub_f32_e32 v22, v22, v21
	v_mov_b32_dpp v109, v72 row_ror:8 row_mask:0xf bank_mask:0xf bound_ctrl:1
	v_max_f32_e32 v109, v109, v109
	v_max_f32_e32 v72, v72, v109
	v_max_f32_e32 v109, v36, v30
	v_max3_f32 v109, v109, v70, v74
	v_max3_f32 v109, v109, v106, v110
	v_max3_f32 v109, v109, v112, v113
	v_max3_f32 v109, v109, v114, v18
	v_sub_f32_e32 v29, v29, v72
	v_mul_f32_e32 v29, 0x3fb8aa3b, v29
	v_mov_b32_dpp v114, v109 quad_perm:[1,0,3,2] row_mask:0xf bank_mask:0xf bound_ctrl:1
	v_max_f32_e32 v114, v114, v114
	v_max_f32_e32 v109, v109, v114
	v_exp_f32_e32 v29, v29
	v_mul_f32_e32 v22, 0x3fb8aa3b, v22
	v_mov_b32_dpp v114, v109 quad_perm:[2,3,0,1] row_mask:0xf bank_mask:0xf bound_ctrl:1
	v_max_f32_e32 v114, v114, v114
	v_max_f32_e32 v109, v109, v114
	v_exp_f32_e32 v22, v22
	v_sub_f32_e32 v69, v69, v72
	v_mov_b32_dpp v114, v109 row_ror:4 row_mask:0xf bank_mask:0xf bound_ctrl:1
	v_max_f32_e32 v114, v114, v114
	v_max_f32_e32 v109, v109, v114
	v_mul_f32_e32 v69, 0x3fb8aa3b, v69
	v_exp_f32_e32 v69, v69
	v_mov_b32_dpp v114, v109 row_ror:8 row_mask:0xf bank_mask:0xf bound_ctrl:1
	v_max_f32_e32 v114, v114, v114
	v_max_f32_e32 v132, v109, v114
	v_max_f32_e32 v109, v36, v31
	v_max3_f32 v109, v109, v71, v75
	v_mul_f32_e32 v114, 0x3e000000, v115
	v_mul_f32_e32 v115, 0x3e000000, v119
	v_max3_f32 v109, v109, v107, v111
	v_cndmask_b32_e64 v114, v96, v114, s[22:23]
	v_cndmask_b32_e64 v115, v96, v115, s[22:23]
	v_max3_f32 v109, v109, v114, v115
	v_max3_f32 v109, v109, v116, v19
	v_sub_f32_e32 v18, v18, v132
	v_mul_f32_e32 v18, 0x3fb8aa3b, v18
	v_mov_b32_dpp v116, v109 quad_perm:[1,0,3,2] row_mask:0xf bank_mask:0xf bound_ctrl:1
	v_max_f32_e32 v116, v116, v116
	v_max_f32_e32 v109, v109, v116
	v_exp_f32_e32 v137, v18
	v_sub_f32_e32 v30, v30, v132
	v_mov_b32_dpp v116, v109 quad_perm:[2,3,0,1] row_mask:0xf bank_mask:0xf bound_ctrl:1
	v_max_f32_e32 v116, v116, v116
	v_max_f32_e32 v109, v109, v116
	v_mul_f32_e32 v30, 0x3fb8aa3b, v30
	v_exp_f32_e32 v30, v30
	v_mov_b32_dpp v116, v109 row_ror:4 row_mask:0xf bank_mask:0xf bound_ctrl:1
	v_max_f32_e32 v116, v116, v116
	v_max_f32_e32 v109, v109, v116
	v_sub_f32_e32 v70, v70, v132
	v_mul_f32_e32 v70, 0x3fb8aa3b, v70
	v_mov_b32_dpp v116, v109 row_ror:8 row_mask:0xf bank_mask:0xf bound_ctrl:1
	v_max_f32_e32 v116, v116, v116
	v_max_f32_e32 v133, v109, v116
	v_sub_f32_e32 v18, v31, v133
	v_mul_f32_e32 v18, 0x3fb8aa3b, v18
	v_exp_f32_e32 v31, v18
	v_sub_f32_e32 v18, v71, v133
	v_mul_f32_e32 v18, 0x3fb8aa3b, v18
	v_exp_f32_e32 v138, v18
	v_sub_f32_e32 v18, v75, v133
	v_mul_f32_e32 v18, 0x3fb8aa3b, v18
	v_exp_f32_e32 v139, v18
	v_sub_f32_e32 v18, v107, v133
	v_mul_f32_e32 v18, 0x3fb8aa3b, v18
	v_exp_f32_e32 v140, v18
	v_sub_f32_e32 v18, v111, v133
	v_mul_f32_e32 v18, 0x3fb8aa3b, v18
	v_exp_f32_e32 v141, v18
	v_sub_f32_e32 v18, v114, v133
	v_mul_f32_e32 v18, 0x3fb8aa3b, v18
	v_exp_f32_e32 v142, v18
	v_sub_f32_e32 v18, v115, v133
	v_mul_f32_e32 v18, 0x3fb8aa3b, v18
	v_exp_f32_e32 v143, v18
	v_fma_f32 v18, v27, s42, -v133
	v_mul_f32_e32 v18, 0x3fb8aa3b, v18
	v_exp_f32_e32 v144, v18
	v_sub_f32_e32 v18, v19, v133
	v_mul_f32_e32 v18, 0x3fb8aa3b, v18
	v_exp_f32_e32 v145, v18
	v_bfe_u32 v18, v20, 16, 1
	v_add3_u32 v18, v20, v18, s43
	ds_write_b16_d16_hi v86, v18
	v_bfe_u32 v18, v29, 16, 1
	v_add3_u32 v18, v29, v18, s43
	ds_write_b16_d16_hi v87, v18
	v_bfe_u32 v18, v30, 16, 1
	v_add3_u32 v18, v30, v18, s43
	ds_write_b16_d16_hi v87, v18 offset:336
	v_bfe_u32 v18, v31, 16, 1
	v_add3_u32 v18, v31, v18, s43
	v_exp_f32_e32 v128, v70
	ds_write_b16_d16_hi v87, v18 offset:672
	v_bfe_u32 v18, v22, 16, 1
	v_add3_u32 v18, v22, v18, s43
	v_sub_f32_e32 v23, v23, v21
	ds_write_b16_d16_hi v86, v18 offset:32
	v_bfe_u32 v18, v69, 16, 1
	v_mul_f32_e32 v23, 0x3fb8aa3b, v23
	v_add3_u32 v18, v69, v18, s43
	v_exp_f32_e32 v23, v23
	v_sub_f32_e32 v73, v73, v72
	ds_write_b16_d16_hi v87, v18 offset:32
	v_bfe_u32 v18, v128, 16, 1
	v_mul_f32_e32 v73, 0x3fb8aa3b, v73
	v_add3_u32 v18, v128, v18, s43
	v_exp_f32_e32 v73, v73
	v_sub_f32_e32 v70, v74, v132
	ds_write_b16_d16_hi v87, v18 offset:368
	v_bfe_u32 v18, v138, 16, 1
	v_mul_f32_e32 v70, 0x3fb8aa3b, v70
	v_add3_u32 v18, v138, v18, s43
	v_exp_f32_e32 v129, v70
	ds_write_b16_d16_hi v87, v18 offset:704
	v_bfe_u32 v18, v23, 16, 1
	v_add3_u32 v18, v23, v18, s43
	v_sub_f32_e32 v28, v28, v21
	ds_write_b16_d16_hi v86, v18 offset:64
	v_bfe_u32 v18, v73, 16, 1
	v_mul_f32_e32 v28, 0x3fb8aa3b, v28
	v_add3_u32 v18, v73, v18, s43
	v_exp_f32_e32 v28, v28
	v_sub_f32_e32 v97, v97, v72
	ds_write_b16_d16_hi v87, v18 offset:64
	v_bfe_u32 v18, v129, 16, 1
	v_mul_f32_e32 v97, 0x3fb8aa3b, v97
	v_add3_u32 v18, v129, v18, s43
	v_exp_f32_e32 v97, v97
	v_sub_f32_e32 v70, v106, v132
	ds_write_b16_d16_hi v87, v18 offset:400
	v_bfe_u32 v18, v139, 16, 1
	v_mul_f32_e32 v70, 0x3fb8aa3b, v70
	v_add3_u32 v18, v139, v18, s43
	v_exp_f32_e32 v130, v70
	ds_write_b16_d16_hi v87, v18 offset:736
	v_bfe_u32 v18, v28, 16, 1
	v_add3_u32 v18, v28, v18, s43
	v_sub_f32_e32 v37, v37, v21
	ds_write_b16_d16_hi v86, v18 offset:96
	v_bfe_u32 v18, v97, 16, 1
	v_mul_f32_e32 v37, 0x3fb8aa3b, v37
	v_add3_u32 v18, v97, v18, s43
	v_exp_f32_e32 v37, v37
	v_sub_f32_e32 v104, v104, v72
	ds_write_b16_d16_hi v87, v18 offset:96
	v_bfe_u32 v18, v130, 16, 1
	v_mul_f32_e32 v104, 0x3fb8aa3b, v104
	v_add3_u32 v18, v130, v18, s43
	v_exp_f32_e32 v104, v104
	v_sub_f32_e32 v70, v110, v132
	ds_write_b16_d16_hi v87, v18 offset:432
	v_bfe_u32 v18, v140, 16, 1
	v_mul_f32_e32 v70, 0x3fb8aa3b, v70
	v_add3_u32 v18, v140, v18, s43
	v_exp_f32_e32 v131, v70
	ds_write_b16_d16_hi v87, v18 offset:768
	v_bfe_u32 v18, v37, 16, 1
	v_add3_u32 v18, v37, v18, s43
	v_sub_f32_e32 v67, v67, v21
	ds_write_b16_d16_hi v86, v18 offset:128
	v_bfe_u32 v18, v104, 16, 1
	v_mul_f32_e32 v67, 0x3fb8aa3b, v67
	v_add3_u32 v18, v104, v18, s43
	v_exp_f32_e32 v67, v67
	v_sub_f32_e32 v105, v105, v72
	ds_write_b16_d16_hi v87, v18 offset:128
	v_bfe_u32 v18, v131, 16, 1
	v_mul_f32_e32 v105, 0x3fb8aa3b, v105
	v_add3_u32 v18, v131, v18, s43
	v_exp_f32_e32 v105, v105
	v_sub_f32_e32 v70, v112, v132
	ds_write_b16_d16_hi v87, v18 offset:464
	v_bfe_u32 v18, v141, 16, 1
	v_mul_f32_e32 v70, 0x3fb8aa3b, v70
	v_add3_u32 v18, v141, v18, s43
	v_exp_f32_e32 v134, v70
	ds_write_b16_d16_hi v87, v18 offset:800
	v_bfe_u32 v18, v67, 16, 1
	v_add3_u32 v18, v67, v18, s43
	v_sub_f32_e32 v68, v68, v21
	ds_write_b16_d16_hi v86, v18 offset:160
	v_bfe_u32 v18, v105, 16, 1
	v_mul_f32_e32 v68, 0x3fb8aa3b, v68
	v_add3_u32 v18, v105, v18, s43
	v_exp_f32_e32 v68, v68
	v_sub_f32_e32 v108, v108, v72
	ds_write_b16_d16_hi v87, v18 offset:160
	v_bfe_u32 v18, v134, 16, 1
	v_mul_f32_e32 v108, 0x3fb8aa3b, v108
	v_add3_u32 v18, v134, v18, s43
	v_exp_f32_e32 v108, v108
	v_sub_f32_e32 v70, v113, v132
	ds_write_b16_d16_hi v87, v18 offset:496
	v_bfe_u32 v18, v142, 16, 1
	v_mul_f32_e32 v70, 0x3fb8aa3b, v70
	v_add3_u32 v18, v142, v18, s43
	v_exp_f32_e32 v135, v70
	ds_write_b16_d16_hi v87, v18 offset:832
	v_bfe_u32 v18, v68, 16, 1
	v_add3_u32 v18, v68, v18, s43
	v_fma_f32 v24, v24, s42, -v21
	ds_write_b16_d16_hi v86, v18 offset:192
	v_bfe_u32 v18, v108, 16, 1
	v_add_f32_e32 v109, 0, v20
	v_mul_f32_e32 v24, 0x3fb8aa3b, v24
	v_add3_u32 v18, v108, v18, s43
	v_add_f32_e32 v109, v22, v109
	v_exp_f32_e32 v116, v24
	v_fma_f32 v25, v25, s42, -v72
	ds_write_b16_d16_hi v87, v18 offset:192
	v_bfe_u32 v18, v135, 16, 1
	v_add_f32_e32 v109, v23, v109
	v_sub_f32_e32 v16, v16, v21
	v_mul_f32_e32 v25, 0x3fb8aa3b, v25
	v_add3_u32 v18, v135, v18, s43
	v_add_f32_e32 v109, v28, v109
	v_mul_f32_e32 v16, 0x3fb8aa3b, v16
	v_exp_f32_e32 v25, v25
	v_fma_f32 v26, v26, s42, -v132
	ds_write_b16_d16_hi v87, v18 offset:528
	v_bfe_u32 v18, v143, 16, 1
	v_add_f32_e32 v109, v37, v109
	v_exp_f32_e32 v16, v16
	v_mul_f32_e32 v26, 0x3fb8aa3b, v26
	v_add3_u32 v18, v143, v18, s43
	v_add_f32_e32 v24, v67, v109
	v_exp_f32_e32 v136, v26
	ds_write_b16_d16_hi v87, v18 offset:864
	v_bfe_u32 v18, v116, 16, 1
	v_add_f32_e32 v24, v68, v24
	v_add3_u32 v18, v116, v18, s43
	v_add_f32_e32 v24, v116, v24
	v_sub_f32_e32 v21, v35, v21
	ds_write_b16_d16_hi v86, v18 offset:224
	v_bfe_u32 v18, v25, 16, 1
	v_add_f32_e32 v24, v16, v24
	v_mul_f32_e32 v21, 0x3fb8aa3b, v21
	v_add3_u32 v18, v25, v18, s43
	v_add_f32_dpp v24, v24, v24 quad_perm:[1,0,3,2] row_mask:0xf bank_mask:0xf bound_ctrl:1
	v_exp_f32_e32 v21, v21
	v_sub_f32_e32 v17, v17, v72
	ds_write_b16_d16_hi v87, v18 offset:224
	v_bfe_u32 v18, v136, 16, 1
	v_add_f32_dpp v24, v24, v24 quad_perm:[2,3,0,1] row_mask:0xf bank_mask:0xf bound_ctrl:1
	v_mul_f32_e32 v17, 0x3fb8aa3b, v17
	v_add3_u32 v18, v136, v18, s43
	v_add_f32_dpp v24, v24, v24 row_ror:4 row_mask:0xf bank_mask:0xf bound_ctrl:1
	v_exp_f32_e32 v17, v17
	ds_write_b16_d16_hi v87, v18 offset:560
	v_bfe_u32 v18, v144, 16, 1
	v_add_f32_dpp v24, v24, v24 row_ror:8 row_mask:0xf bank_mask:0xf bound_ctrl:1
	v_add3_u32 v18, v144, v18, s43
	v_add_f32_e32 v24, v21, v24
	v_add_f32_e32 v21, 0, v29
	ds_write_b16_d16_hi v87, v18 offset:896
	v_bfe_u32 v18, v16, 16, 1
	v_add_f32_e32 v21, v69, v21
	v_add3_u32 v16, v16, v18, s43
	v_add_f32_e32 v21, v73, v21
	ds_write_b16_d16_hi v86, v16 offset:256
	v_bfe_u32 v16, v17, 16, 1
	v_add_f32_e32 v21, v97, v21
	v_add3_u32 v16, v17, v16, s43
	v_add_f32_e32 v21, v104, v21
	ds_write_b16_d16_hi v87, v16 offset:256
	v_bfe_u32 v16, v137, 16, 1
	v_add_f32_e32 v21, v105, v21
	v_add3_u32 v16, v137, v16, s43
	v_add_f32_e32 v21, v108, v21
	ds_write_b16_d16_hi v87, v16 offset:592
	v_bfe_u32 v16, v145, 16, 1
	v_add_f32_e32 v21, v25, v21
	v_add3_u32 v16, v145, v16, s43
	v_add_f32_e32 v21, v17, v21
	ds_write_b16_d16_hi v87, v16 offset:928
	ds_read_b128 v[16:19], v88
	v_add_f32_dpp v21, v21, v21 quad_perm:[1,0,3,2] row_mask:0xf bank_mask:0xf bound_ctrl:1
	v_sub_f32_e32 v26, v35, v72
	v_mul_f32_e32 v37, 0x3fb8aa3b, v26
	v_add_f32_dpp v21, v21, v21 quad_perm:[2,3,0,1] row_mask:0xf bank_mask:0xf bound_ctrl:1
	v_add_f32_e32 v30, 0, v30
	v_add_f32_e32 v30, v128, v30
	v_add_f32_dpp v20, v21, v21 row_ror:4 row_mask:0xf bank_mask:0xf bound_ctrl:1
	v_add_f32_e32 v30, v129, v30
	v_add_f32_e32 v30, v130, v30
	v_add_f32_dpp v25, v20, v20 row_ror:8 row_mask:0xf bank_mask:0xf bound_ctrl:1
	ds_read_b128 v[20:23], v91 offset:36864
	ds_read_b128 v[26:29], v91 offset:45824
	ds_read_b128 v[68:71], v88 offset:64
	ds_read_b128 v[72:75], v88 offset:256
	s_waitcnt lgkmcnt(3)
	v_mfma_f32_16x16x32_bf16 v[20:23], v[16:19], v[20:23], 0
	ds_read_b128 v[104:107], v91 offset:54784
	ds_read_b128 v[108:111], v91 offset:45888
	ds_read_b128 v[112:115], v91 offset:63744
	ds_read_b128 v[116:119], v91 offset:46080
	ds_read_b128 v[120:123], v91 offset:36928
	ds_read_b128 v[124:127], v91 offset:63808
	s_waitcnt lgkmcnt(8)
	v_mfma_f32_16x16x32_bf16 v[26:29], v[16:19], v[26:29], 0
	v_add_f32_e32 v30, v131, v30
	v_add_f32_e32 v31, 0, v31
	v_add_f32_e32 v31, v138, v31
	s_waitcnt lgkmcnt(5)
	v_mfma_f32_16x16x32_bf16 v[104:107], v[16:19], v[104:107], 0
	v_add_f32_e32 v31, v139, v31
	v_add_f32_e32 v31, v140, v31
	v_exp_f32_e32 v37, v37
	s_waitcnt lgkmcnt(3)
	v_mfma_f32_16x16x32_bf16 v[16:19], v[16:19], v[112:115], 0
	ds_read_b128 v[112:115], v91 offset:36992
	v_add_f32_e32 v31, v141, v31
	v_add_f32_e32 v31, v142, v31
	s_waitcnt lgkmcnt(2)
	v_mfma_f32_16x16x32_bf16 v[20:23], v[68:71], v[120:123], v[20:23]
	ds_read_b128 v[120:123], v91 offset:54848
	v_add_f32_e32 v30, v134, v30
	v_add_f32_e32 v31, v143, v31
	v_mfma_f32_16x16x32_bf16 v[26:29], v[68:71], v[108:111], v[26:29]
	ds_read_b128 v[108:111], v88 offset:128
	ds_read_b128 v[128:131], v91 offset:54912
	v_add_f32_e32 v30, v135, v30
	v_add_f32_e32 v31, v144, v31
	s_waitcnt lgkmcnt(2)
	v_mfma_f32_16x16x32_bf16 v[104:107], v[68:71], v[120:123], v[104:107]
	v_add_f32_e32 v25, v37, v25
	v_add_f32_e32 v30, v136, v30
	v_sub_f32_e32 v37, v35, v132
	v_mfma_f32_16x16x32_bf16 v[16:19], v[68:71], v[124:127], v[16:19]
	ds_read_b128 v[68:71], v91 offset:45952
	ds_read_b128 v[120:123], v88 offset:192
	v_add_f32_e32 v31, v145, v31
	v_add_f32_e32 v30, v137, v30
	s_waitcnt lgkmcnt(3)
	v_mfma_f32_16x16x32_bf16 v[20:23], v[108:111], v[112:115], v[20:23]
	ds_read_b128 v[112:115], v91 offset:46016
	v_mul_f32_e32 v37, 0x3fb8aa3b, v37
	v_add_f32_dpp v31, v31, v31 quad_perm:[1,0,3,2] row_mask:0xf bank_mask:0xf bound_ctrl:1
	s_waitcnt lgkmcnt(2)
	v_mfma_f32_16x16x32_bf16 v[26:29], v[108:111], v[68:71], v[26:29]
	ds_read_b128 v[68:71], v91 offset:63872
	v_add_f32_dpp v30, v30, v30 quad_perm:[1,0,3,2] row_mask:0xf bank_mask:0xf bound_ctrl:1
	v_exp_f32_e32 v37, v37
	v_mfma_f32_16x16x32_bf16 v[104:107], v[108:111], v[128:131], v[104:107]
	ds_read_b128 v[124:127], v91 offset:37056
	ds_read_b128 v[128:131], v91 offset:63936
	v_add_f32_dpp v30, v30, v30 quad_perm:[2,3,0,1] row_mask:0xf bank_mask:0xf bound_ctrl:1
	s_waitcnt lgkmcnt(2)
	v_mfma_f32_16x16x32_bf16 v[16:19], v[108:111], v[68:71], v[16:19]
	ds_read_b128 v[68:71], v91 offset:37120
	ds_read_b128 v[108:111], v91 offset:54976
	v_add_f32_dpp v30, v30, v30 row_ror:4 row_mask:0xf bank_mask:0xf bound_ctrl:1
	s_waitcnt lgkmcnt(3)
	v_mfma_f32_16x16x32_bf16 v[20:23], v[120:123], v[124:127], v[20:23]
	v_add_f32_dpp v30, v30, v30 row_ror:8 row_mask:0xf bank_mask:0xf bound_ctrl:1
	v_add_f32_e32 v30, v37, v30
	s_waitcnt lgkmcnt(1)
	v_mfma_f32_16x16x32_bf16 v[68:71], v[72:75], v[68:71], v[20:23]
	v_mfma_f32_16x16x32_bf16 v[26:29], v[120:123], v[112:115], v[26:29]
	s_nop 2
	v_add_f32_dpp v20, v31, v31 quad_perm:[2,3,0,1] row_mask:0xf bank_mask:0xf bound_ctrl:1
	ds_read_b128 v[112:115], v91 offset:55040
	s_nop 1
	v_add_f32_dpp v20, v20, v20 row_ror:4 row_mask:0xf bank_mask:0xf bound_ctrl:1
	v_mfma_f32_16x16x32_bf16 v[16:19], v[120:123], v[128:131], v[16:19]
	v_add_f32_dpp v31, v20, v20 row_ror:8 row_mask:0xf bank_mask:0xf bound_ctrl:1
	v_sub_f32_e32 v20, v35, v133
	v_mul_f32_e32 v20, 0x3fb8aa3b, v20
	v_exp_f32_e32 v37, v20
	ds_read_b128 v[20:23], v91 offset:64000
	s_waitcnt lgkmcnt(0)
	v_mfma_f32_16x16x32_bf16 v[16:19], v[72:75], v[20:23], v[16:19]
	v_add_f32_e32 v31, v37, v31
	v_or_b32_e32 v20, v34, v60
	v_mad_u64_u32 v[20:21], s[52:53], v20, s44, v[32:33]
	v_add_u32_e32 v21, s10, v21
	v_add_co_u32_e32 v22, vcc, 0x1000, v20
	v_mfma_f32_16x16x32_bf16 v[26:29], v[72:75], v[116:119], v[26:29]
	s_nop 0
	v_addc_co_u32_e32 v23, vcc, 0, v21, vcc
	v_mfma_f32_16x16x32_bf16 v[104:107], v[120:123], v[108:111], v[104:107]
	v_mfma_f32_16x16x32_bf16 v[104:107], v[72:75], v[112:115], v[104:107]
	s_nop 1
	v_rcp_f32_e32 v194, v24
	v_rcp_f32_e32 v195, v25
	v_rcp_f32_e32 v196, v30
	v_rcp_f32_e32 v197, v31
	s_nop 0
	v_fma_f32 v240, -v24, v194, 1.0
	v_fma_f32 v241, -v25, v195, 1.0
	v_fma_f32 v242, -v30, v196, 1.0
	v_fma_f32 v243, -v31, v197, 1.0
	v_fmac_f32_e32 v194, v240, v194
	v_fmac_f32_e32 v195, v241, v195
	v_fmac_f32_e32 v196, v242, v196
	v_fmac_f32_e32 v197, v243, v197
	v_fma_f32 v240, -v24, v194, 1.0
	v_fma_f32 v241, -v25, v195, 1.0
	v_fma_f32 v242, -v30, v196, 1.0
	v_fma_f32 v243, -v31, v197, 1.0
	v_fmac_f32_e32 v194, v240, v194
	v_fmac_f32_e32 v195, v241, v195
	v_fmac_f32_e32 v196, v242, v196
	v_fmac_f32_e32 v197, v243, v197
	v_mul_f32_e32 v198, v68, v194
	v_mul_f32_e32 v199, v69, v195
	v_mul_f32_e32 v200, v70, v196
	v_mul_f32_e32 v201, v71, v197
	v_mul_f32_e32 v202, v26, v194
	v_mul_f32_e32 v203, v27, v195
	v_mul_f32_e32 v204, v28, v196
	v_mul_f32_e32 v205, v29, v197
	v_mul_f32_e32 v206, v104, v194
	v_mul_f32_e32 v207, v105, v195
	v_mul_f32_e32 v208, v106, v196
	v_mul_f32_e32 v209, v107, v197
	v_mul_f32_e32 v210, v16, v194
	v_mul_f32_e32 v211, v17, v195
	v_mul_f32_e32 v212, v18, v196
	v_mul_f32_e32 v213, v19, v197
	v_and_b32_e32 v240, 3, v174
	v_mul_u32_u24_e32 v240, 0x87e, v240
	v_mov_b32_e32 v241, 0
	v_lshl_add_u64 v[238:239], v[20:21], 0, v[240:241]
	s_mov_b32 vcc_lo, 0x55555555
	s_mov_b32 vcc_hi, 0x55555555
	s_nop 1
	v_cndmask_b32_dpp v214, v199, v198, vcc quad_perm:[1,0,3,2] row_mask:0xf bank_mask:0xf
	v_cndmask_b32_dpp v216, v201, v200, vcc quad_perm:[1,0,3,2] row_mask:0xf bank_mask:0xf
	v_cndmask_b32_dpp v218, v203, v202, vcc quad_perm:[1,0,3,2] row_mask:0xf bank_mask:0xf
	v_cndmask_b32_dpp v220, v205, v204, vcc quad_perm:[1,0,3,2] row_mask:0xf bank_mask:0xf
	v_cndmask_b32_dpp v222, v207, v206, vcc quad_perm:[1,0,3,2] row_mask:0xf bank_mask:0xf
	v_cndmask_b32_dpp v224, v209, v208, vcc quad_perm:[1,0,3,2] row_mask:0xf bank_mask:0xf
	v_cndmask_b32_dpp v226, v211, v210, vcc quad_perm:[1,0,3,2] row_mask:0xf bank_mask:0xf
	v_cndmask_b32_dpp v228, v213, v212, vcc quad_perm:[1,0,3,2] row_mask:0xf bank_mask:0xf
	s_mov_b32 vcc_lo, 0xaaaaaaaa
	s_mov_b32 vcc_hi, 0xaaaaaaaa
	s_nop 1
	v_cndmask_b32_dpp v215, v198, v199, vcc quad_perm:[1,0,3,2] row_mask:0xf bank_mask:0xf
	v_cndmask_b32_dpp v217, v200, v201, vcc quad_perm:[1,0,3,2] row_mask:0xf bank_mask:0xf
	v_cndmask_b32_dpp v219, v202, v203, vcc quad_perm:[1,0,3,2] row_mask:0xf bank_mask:0xf
	v_cndmask_b32_dpp v221, v204, v205, vcc quad_perm:[1,0,3,2] row_mask:0xf bank_mask:0xf
	v_cndmask_b32_dpp v223, v206, v207, vcc quad_perm:[1,0,3,2] row_mask:0xf bank_mask:0xf
	v_cndmask_b32_dpp v225, v208, v209, vcc quad_perm:[1,0,3,2] row_mask:0xf bank_mask:0xf
	v_cndmask_b32_dpp v227, v210, v211, vcc quad_perm:[1,0,3,2] row_mask:0xf bank_mask:0xf
	v_cndmask_b32_dpp v229, v212, v213, vcc quad_perm:[1,0,3,2] row_mask:0xf bank_mask:0xf
	s_mov_b32 vcc_lo, 0x33333333
	s_mov_b32 vcc_hi, 0x33333333
	s_nop 1
	v_cndmask_b32_dpp v198, v216, v214, vcc quad_perm:[2,3,0,1] row_mask:0xf bank_mask:0xf
	v_cndmask_b32_dpp v199, v217, v215, vcc quad_perm:[2,3,0,1] row_mask:0xf bank_mask:0xf
	v_cndmask_b32_dpp v202, v220, v218, vcc quad_perm:[2,3,0,1] row_mask:0xf bank_mask:0xf
	v_cndmask_b32_dpp v203, v221, v219, vcc quad_perm:[2,3,0,1] row_mask:0xf bank_mask:0xf
	v_cndmask_b32_dpp v206, v224, v222, vcc quad_perm:[2,3,0,1] row_mask:0xf bank_mask:0xf
	v_cndmask_b32_dpp v207, v225, v223, vcc quad_perm:[2,3,0,1] row_mask:0xf bank_mask:0xf
	v_cndmask_b32_dpp v210, v228, v226, vcc quad_perm:[2,3,0,1] row_mask:0xf bank_mask:0xf
	v_cndmask_b32_dpp v211, v229, v227, vcc quad_perm:[2,3,0,1] row_mask:0xf bank_mask:0xf
	s_mov_b32 vcc_lo, 0xcccccccc
	s_mov_b32 vcc_hi, 0xcccccccc
	s_nop 1
	v_cndmask_b32_dpp v200, v214, v216, vcc quad_perm:[2,3,0,1] row_mask:0xf bank_mask:0xf
	v_cndmask_b32_dpp v201, v215, v217, vcc quad_perm:[2,3,0,1] row_mask:0xf bank_mask:0xf
	v_cndmask_b32_dpp v204, v218, v220, vcc quad_perm:[2,3,0,1] row_mask:0xf bank_mask:0xf
	v_cndmask_b32_dpp v205, v219, v221, vcc quad_perm:[2,3,0,1] row_mask:0xf bank_mask:0xf
	v_cndmask_b32_dpp v208, v222, v224, vcc quad_perm:[2,3,0,1] row_mask:0xf bank_mask:0xf
	v_cndmask_b32_dpp v209, v223, v225, vcc quad_perm:[2,3,0,1] row_mask:0xf bank_mask:0xf
	v_cndmask_b32_dpp v212, v226, v228, vcc quad_perm:[2,3,0,1] row_mask:0xf bank_mask:0xf
	v_cndmask_b32_dpp v213, v227, v229, vcc quad_perm:[2,3,0,1] row_mask:0xf bank_mask:0xf
	v_cvt_pk_bf16_f32 v230, v198, v199
	v_cvt_pk_bf16_f32 v231, v200, v201
	v_cvt_pk_bf16_f32 v232, v202, v203
	v_cvt_pk_bf16_f32 v233, v204, v205
	v_cvt_pk_bf16_f32 v234, v206, v207
	v_cvt_pk_bf16_f32 v235, v208, v209
	v_cvt_pk_bf16_f32 v236, v210, v211
	v_cvt_pk_bf16_f32 v237, v212, v213
	global_store_dwordx2 v[238:239], v[230:231], off offset:0
	global_store_dwordx2 v[238:239], v[232:233], off offset:32
	global_store_dwordx2 v[238:239], v[234:235], off offset:64
	global_store_dwordx2 v[238:239], v[236:237], off offset:96
	ds_read_b128 v[16:19], v92
	ds_read_b128 v[20:23], v92 offset:64
	s_waitcnt lgkmcnt(1)
	v_mfma_f32_16x16x32_bf16 v[16:19], v[8:11], v[16:19], 0
	s_waitcnt lgkmcnt(0)
	v_mfma_f32_16x16x32_bf16 v[24:27], v[12:15], v[20:23], v[16:19]
	s_nop 5
	ds_read_b128 v[16:19], v92 offset:2304
	ds_read_b128 v[20:23], v92 offset:2368
	v_mul_f32_e32 v25, 0x3e000000, v25
	s_waitcnt lgkmcnt(1)
	v_mfma_f32_16x16x32_bf16 v[16:19], v[8:11], v[16:19], 0
	v_cndmask_b32_e64 v25, v96, v25, s[26:27]
	v_mul_f32_e32 v26, 0x3e000000, v26
	v_cndmask_b32_e64 v26, v96, v26, s[28:29]
	s_waitcnt lgkmcnt(0)
	v_mfma_f32_16x16x32_bf16 v[28:31], v[12:15], v[20:23], v[16:19]
	s_nop 2
	ds_read_b128 v[16:19], v92 offset:4608
	ds_read_b128 v[20:23], v92 offset:4672
	v_mul_f32_e32 v27, 0x3e000000, v27
	v_cndmask_b32_e64 v27, v96, v27, s[30:31]
	s_waitcnt lgkmcnt(1)
	v_mfma_f32_16x16x32_bf16 v[16:19], v[8:11], v[16:19], 0
	v_mul_f32_e32 v29, 0x3e000000, v29
	v_cndmask_b32_e64 v29, v96, v29, s[34:35]
	v_mul_f32_e32 v30, 0x3e000000, v30
	s_waitcnt lgkmcnt(0)
	v_mfma_f32_16x16x32_bf16 v[68:71], v[12:15], v[20:23], v[16:19]
	s_nop 2
	ds_read_b128 v[16:19], v92 offset:6912
	ds_read_b128 v[20:23], v92 offset:6976
	v_cndmask_b32_e64 v30, v96, v30, s[34:35]
	v_mul_f32_e32 v31, 0x3e000000, v31
	s_waitcnt lgkmcnt(1)
	v_mfma_f32_16x16x32_bf16 v[16:19], v[8:11], v[16:19], 0
	v_mul_f32_e32 v70, 0x3e000000, v70
	v_cndmask_b32_e64 v70, v96, v70, s[22:23]
	v_mul_f32_e32 v71, 0x3e000000, v71
	s_waitcnt lgkmcnt(0)
	v_mfma_f32_16x16x32_bf16 v[72:75], v[12:15], v[20:23], v[16:19]
	s_nop 2
	ds_read_b128 v[16:19], v92 offset:9216
	ds_read_b128 v[20:23], v92 offset:9280
	v_cndmask_b32_e64 v31, v96, v31, s[34:35]
	v_cndmask_b32_e64 v71, v96, v71, s[22:23]
	s_waitcnt lgkmcnt(1)
	v_mfma_f32_16x16x32_bf16 v[16:19], v[8:11], v[16:19], 0
	v_mul_f32_e32 v74, 0x3e000000, v74
	v_cndmask_b32_e64 v74, v96, v74, s[22:23]
	v_mul_f32_e32 v75, 0x3e000000, v75
	s_waitcnt lgkmcnt(0)
	v_mfma_f32_16x16x32_bf16 v[104:107], v[12:15], v[20:23], v[16:19]
	s_nop 2
	ds_read_b128 v[16:19], v92 offset:11520
	ds_read_b128 v[20:23], v92 offset:11584
	v_cndmask_b32_e64 v75, v96, v75, s[22:23]
	s_nop 1
	v_mul_f32_e32 v107, 0x3e000000, v107
	s_waitcnt lgkmcnt(1)
	v_mfma_f32_16x16x32_bf16 v[16:19], v[8:11], v[16:19], 0
	v_cndmask_b32_e64 v107, v96, v107, s[22:23]
	s_waitcnt lgkmcnt(0)
	v_mfma_f32_16x16x32_bf16 v[108:111], v[12:15], v[20:23], v[16:19]
	s_nop 4
	ds_read_b128 v[16:19], v92 offset:13824
	ds_read_b128 v[20:23], v92 offset:13888
	s_nop 0
	v_mul_f32_e32 v37, 0x3e000000, v108
	s_waitcnt lgkmcnt(1)
	v_mfma_f32_16x16x32_bf16 v[16:19], v[8:11], v[16:19], 0
	v_cndmask_b32_e64 v37, v96, v37, s[22:23]
	v_mul_f32_e32 v108, 0x3e000000, v111
	v_cndmask_b32_e64 v108, v96, v108, s[22:23]
	s_waitcnt lgkmcnt(0)
	v_mfma_f32_16x16x32_bf16 v[16:19], v[12:15], v[20:23], v[16:19]
	ds_read_b128 v[20:23], v92 offset:16128
	ds_read_b128 v[112:115], v92 offset:16192
	s_waitcnt lgkmcnt(1)
	v_mfma_f32_16x16x32_bf16 v[20:23], v[8:11], v[20:23], 0
	s_nop 3
	v_mul_f32_e32 v67, 0x3e000000, v16
	v_mul_f32_e32 v97, 0x3e000000, v17
	s_waitcnt lgkmcnt(0)
	v_mfma_f32_16x16x32_bf16 v[20:23], v[12:15], v[112:115], v[20:23]
	ds_read_b128 v[112:115], v92 offset:18432
	ds_read_b128 v[116:119], v92 offset:18496
	s_waitcnt lgkmcnt(1)
	v_mfma_f32_16x16x32_bf16 v[8:11], v[8:11], v[112:115], 0
	s_waitcnt lgkmcnt(0)
	v_mfma_f32_16x16x32_bf16 v[8:11], v[12:15], v[116:119], v[8:11]
	v_mul_f32_e32 v12, 0x3e000000, v24
	v_cndmask_b32_e64 v12, v96, v12, s[24:25]
	v_mul_f32_e32 v14, 0x3e000000, v28
	v_mul_f32_e32 v15, 0x3e000000, v68
	v_max_f32_e32 v13, v36, v12
	v_cndmask_b32_e64 v14, v96, v14, s[34:35]
	v_cndmask_b32_e64 v15, v96, v15, s[22:23]
	v_mul_f32_e32 v24, 0x3e000000, v72
	v_mul_f32_e32 v28, 0x3e000000, v104
	v_max3_f32 v13, v13, v14, v15
	v_cndmask_b32_e64 v24, v96, v24, s[22:23]
	v_cndmask_b32_e64 v28, v96, v28, s[22:23]
	v_max3_f32 v13, v13, v24, v28
	v_mul_f32_e32 v8, 0x3e000000, v8
	v_max3_f32 v13, v13, v37, v67
	v_mul_f32_e32 v67, 0x3e000000, v20
	v_cndmask_b32_e64 v8, v8, v96, s[6:7]
	v_max3_f32 v13, v13, v67, v8
	v_mul_f32_e32 v68, 0x3e000000, v69
	v_cndmask_b32_e64 v68, v96, v68, s[22:23]
	v_mov_b32_dpp v67, v13 quad_perm:[1,0,3,2] row_mask:0xf bank_mask:0xf bound_ctrl:1
	v_max_f32_e32 v67, v67, v67
	v_max_f32_e32 v13, v13, v67
	v_mul_f32_e32 v69, 0x3e000000, v73
	v_mul_f32_e32 v72, 0x3e000000, v105
	v_mov_b32_dpp v67, v13 quad_perm:[2,3,0,1] row_mask:0xf bank_mask:0xf bound_ctrl:1
	v_max_f32_e32 v67, v67, v67
	v_max_f32_e32 v13, v13, v67
	v_cndmask_b32_e64 v69, v96, v69, s[22:23]
	v_cndmask_b32_e64 v72, v96, v72, s[22:23]
	v_mov_b32_dpp v67, v13 row_ror:4 row_mask:0xf bank_mask:0xf bound_ctrl:1
	v_max_f32_e32 v67, v67, v67
	v_max_f32_e32 v13, v13, v67
	v_mul_f32_e32 v73, 0x3e000000, v109
	v_cndmask_b32_e64 v73, v96, v73, s[22:23]
	v_mov_b32_dpp v67, v13 row_ror:8 row_mask:0xf bank_mask:0xf bound_ctrl:1
	v_max_f32_e32 v67, v67, v67
	v_max_f32_e32 v13, v13, v67
	v_max_f32_e32 v67, v36, v25
	v_max3_f32 v67, v67, v29, v68
	v_max3_f32 v67, v67, v69, v72
	v_mul_f32_e32 v9, 0x3e000000, v9
	v_max3_f32 v67, v67, v73, v97
	v_mul_f32_e32 v97, 0x3e000000, v21
	v_cndmask_b32_e64 v9, v9, v96, s[12:13]
	v_max3_f32 v67, v67, v97, v9
	v_mul_f32_e32 v104, 0x3e000000, v106
	v_cndmask_b32_e64 v104, v96, v104, s[22:23]
	v_mov_b32_dpp v97, v67 quad_perm:[1,0,3,2] row_mask:0xf bank_mask:0xf bound_ctrl:1
	v_max_f32_e32 v97, v97, v97
	v_max_f32_e32 v67, v67, v97
	v_mul_f32_e32 v105, 0x3e000000, v110
	v_cndmask_b32_e64 v105, v96, v105, s[22:23]
	v_mov_b32_dpp v97, v67 quad_perm:[2,3,0,1] row_mask:0xf bank_mask:0xf bound_ctrl:1
	v_max_f32_e32 v97, v97, v97
	v_max_f32_e32 v67, v67, v97
	v_mul_f32_e32 v106, 0x3e000000, v18
	v_mul_f32_e32 v10, 0x3e000000, v10
	v_mov_b32_dpp v97, v67 row_ror:4 row_mask:0xf bank_mask:0xf bound_ctrl:1
	v_max_f32_e32 v97, v97, v97
	v_max_f32_e32 v67, v67, v97
	v_cndmask_b32_e64 v10, v10, v96, s[16:17]
	v_mul_f32_e32 v109, 0x3e000000, v19
	v_mov_b32_dpp v97, v67 row_ror:8 row_mask:0xf bank_mask:0xf bound_ctrl:1
	v_max_f32_e32 v97, v97, v97
	v_max_f32_e32 v67, v67, v97
	v_max_f32_e32 v97, v36, v26
	v_max3_f32 v97, v97, v30, v70
	v_max3_f32 v97, v97, v74, v104
	v_max3_f32 v97, v97, v105, v106
	v_mul_f32_e32 v106, 0x3e000000, v22
	v_max3_f32 v97, v97, v106, v10
	v_mul_f32_e32 v11, 0x3e000000, v11
	v_cndmask_b32_e64 v11, v11, v96, s[20:21]
	v_mov_b32_dpp v106, v97 quad_perm:[1,0,3,2] row_mask:0xf bank_mask:0xf bound_ctrl:1
	v_max_f32_e32 v106, v106, v106
	v_max_f32_e32 v97, v97, v106
	v_sub_f32_e32 v12, v12, v13
	v_mul_f32_e32 v12, 0x3fb8aa3b, v12
	v_mov_b32_dpp v106, v97 quad_perm:[2,3,0,1] row_mask:0xf bank_mask:0xf bound_ctrl:1
	v_max_f32_e32 v106, v106, v106
	v_max_f32_e32 v97, v97, v106
	v_exp_f32_e32 v12, v12
	v_sub_f32_e32 v25, v25, v67
	v_mov_b32_dpp v106, v97 row_ror:4 row_mask:0xf bank_mask:0xf bound_ctrl:1
	v_max_f32_e32 v106, v106, v106
	v_max_f32_e32 v97, v97, v106
	v_mul_f32_e32 v25, 0x3fb8aa3b, v25
	v_exp_f32_e32 v25, v25
	v_mov_b32_dpp v106, v97 row_ror:8 row_mask:0xf bank_mask:0xf bound_ctrl:1
	v_max_f32_e32 v106, v106, v106
	v_max_f32_e32 v97, v97, v106
	v_max_f32_e32 v106, v36, v27
	v_max3_f32 v106, v106, v31, v71
	v_max3_f32 v106, v106, v75, v107
	v_max3_f32 v106, v106, v108, v109
	v_mul_f32_e32 v109, 0x3e000000, v23
	v_max3_f32 v106, v106, v109, v11
	v_sub_f32_e32 v10, v10, v97
	v_mul_f32_e32 v10, 0x3fb8aa3b, v10
	v_mov_b32_dpp v109, v106 quad_perm:[1,0,3,2] row_mask:0xf bank_mask:0xf bound_ctrl:1
	v_max_f32_e32 v109, v109, v109
	v_max_f32_e32 v106, v106, v109
	v_exp_f32_e32 v127, v10
	v_sub_f32_e32 v26, v26, v97
	v_mov_b32_dpp v109, v106 quad_perm:[2,3,0,1] row_mask:0xf bank_mask:0xf bound_ctrl:1
	v_max_f32_e32 v109, v109, v109
	v_max_f32_e32 v106, v106, v109
	v_mul_f32_e32 v26, 0x3fb8aa3b, v26
	v_exp_f32_e32 v112, v26
	v_mov_b32_dpp v109, v106 row_ror:4 row_mask:0xf bank_mask:0xf bound_ctrl:1
	v_max_f32_e32 v109, v109, v109
	v_max_f32_e32 v106, v106, v109
	v_sub_f32_e32 v14, v14, v13
	v_mul_f32_e32 v14, 0x3fb8aa3b, v14
	v_mov_b32_dpp v109, v106 row_ror:8 row_mask:0xf bank_mask:0xf bound_ctrl:1
	v_max_f32_e32 v109, v109, v109
	v_max_f32_e32 v124, v106, v109
	v_sub_f32_e32 v10, v27, v124
	v_mul_f32_e32 v10, 0x3fb8aa3b, v10
	v_exp_f32_e32 v128, v10
	v_sub_f32_e32 v10, v31, v124
	v_mul_f32_e32 v10, 0x3fb8aa3b, v10
	v_exp_f32_e32 v31, v10
	v_sub_f32_e32 v10, v71, v124
	v_mul_f32_e32 v10, 0x3fb8aa3b, v10
	v_exp_f32_e32 v129, v10
	v_sub_f32_e32 v10, v75, v124
	v_mul_f32_e32 v10, 0x3fb8aa3b, v10
	v_exp_f32_e32 v130, v10
	v_sub_f32_e32 v10, v107, v124
	v_mul_f32_e32 v10, 0x3fb8aa3b, v10
	v_exp_f32_e32 v131, v10
	v_sub_f32_e32 v10, v108, v124
	v_mul_f32_e32 v10, 0x3fb8aa3b, v10
	v_exp_f32_e32 v132, v10
	v_fma_f32 v10, v19, s42, -v124
	v_mul_f32_e32 v10, 0x3fb8aa3b, v10
	v_exp_f32_e32 v133, v10
	v_fma_f32 v10, v23, s42, -v124
	v_mul_f32_e32 v10, 0x3fb8aa3b, v10
	v_exp_f32_e32 v134, v10
	v_sub_f32_e32 v10, v11, v124
	v_mul_f32_e32 v10, 0x3fb8aa3b, v10
	v_exp_f32_e32 v135, v10
	v_bfe_u32 v10, v12, 16, 1
	v_add3_u32 v10, v12, v10, s43
	ds_write_b16_d16_hi v86, v10
	v_bfe_u32 v10, v25, 16, 1
	v_add3_u32 v10, v25, v10, s43
	v_exp_f32_e32 v14, v14
	v_sub_f32_e32 v29, v29, v67
	ds_write_b16_d16_hi v87, v10
	v_bfe_u32 v10, v112, 16, 1
	v_mul_f32_e32 v29, 0x3fb8aa3b, v29
	v_add3_u32 v10, v112, v10, s43
	v_exp_f32_e32 v29, v29
	v_sub_f32_e32 v26, v30, v97
	ds_write_b16_d16_hi v87, v10 offset:336
	v_bfe_u32 v10, v128, 16, 1
	v_mul_f32_e32 v26, 0x3fb8aa3b, v26
	v_add3_u32 v10, v128, v10, s43
	v_exp_f32_e32 v30, v26
	ds_write_b16_d16_hi v87, v10 offset:672
	v_bfe_u32 v10, v14, 16, 1
	v_add3_u32 v10, v14, v10, s43
	v_sub_f32_e32 v15, v15, v13
	ds_write_b16_d16_hi v86, v10 offset:32
	v_bfe_u32 v10, v29, 16, 1
	v_mul_f32_e32 v15, 0x3fb8aa3b, v15
	v_add3_u32 v10, v29, v10, s43
	v_exp_f32_e32 v15, v15
	v_sub_f32_e32 v68, v68, v67
	ds_write_b16_d16_hi v87, v10 offset:32
	v_bfe_u32 v10, v30, 16, 1
	v_mul_f32_e32 v68, 0x3fb8aa3b, v68
	v_add3_u32 v10, v30, v10, s43
	v_exp_f32_e32 v68, v68
	v_sub_f32_e32 v26, v70, v97
	ds_write_b16_d16_hi v87, v10 offset:368
	v_bfe_u32 v10, v31, 16, 1
	v_mul_f32_e32 v26, 0x3fb8aa3b, v26
	v_add3_u32 v10, v31, v10, s43
	v_exp_f32_e32 v120, v26
	ds_write_b16_d16_hi v87, v10 offset:704
	v_bfe_u32 v10, v15, 16, 1
	v_add3_u32 v10, v15, v10, s43
	v_sub_f32_e32 v24, v24, v13
	ds_write_b16_d16_hi v86, v10 offset:64
	v_bfe_u32 v10, v68, 16, 1
	v_mul_f32_e32 v24, 0x3fb8aa3b, v24
	v_add3_u32 v10, v68, v10, s43
	v_exp_f32_e32 v24, v24
	v_sub_f32_e32 v69, v69, v67
	ds_write_b16_d16_hi v87, v10 offset:64
	v_bfe_u32 v10, v120, 16, 1
	v_mul_f32_e32 v69, 0x3fb8aa3b, v69
	v_add3_u32 v10, v120, v10, s43
	v_exp_f32_e32 v69, v69
	v_sub_f32_e32 v26, v74, v97
	ds_write_b16_d16_hi v87, v10 offset:400
	v_bfe_u32 v10, v129, 16, 1
	v_mul_f32_e32 v26, 0x3fb8aa3b, v26
	v_add3_u32 v10, v129, v10, s43
	v_exp_f32_e32 v121, v26
	ds_write_b16_d16_hi v87, v10 offset:736
	v_bfe_u32 v10, v24, 16, 1
	v_add3_u32 v10, v24, v10, s43
	v_sub_f32_e32 v28, v28, v13
	ds_write_b16_d16_hi v86, v10 offset:96
	v_bfe_u32 v10, v69, 16, 1
	v_mul_f32_e32 v28, 0x3fb8aa3b, v28
	v_add3_u32 v10, v69, v10, s43
	v_exp_f32_e32 v28, v28
	v_sub_f32_e32 v72, v72, v67
	ds_write_b16_d16_hi v87, v10 offset:96
	v_bfe_u32 v10, v121, 16, 1
	v_mul_f32_e32 v72, 0x3fb8aa3b, v72
	v_add3_u32 v10, v121, v10, s43
	v_exp_f32_e32 v72, v72
	v_sub_f32_e32 v26, v104, v97
	ds_write_b16_d16_hi v87, v10 offset:432
	v_bfe_u32 v10, v130, 16, 1
	v_mul_f32_e32 v26, 0x3fb8aa3b, v26
	v_add3_u32 v10, v130, v10, s43
	v_exp_f32_e32 v122, v26
	ds_write_b16_d16_hi v87, v10 offset:768
	v_bfe_u32 v10, v28, 16, 1
	v_add3_u32 v10, v28, v10, s43
	v_sub_f32_e32 v37, v37, v13
	ds_write_b16_d16_hi v86, v10 offset:128
	v_bfe_u32 v10, v72, 16, 1
	v_mul_f32_e32 v37, 0x3fb8aa3b, v37
	v_add3_u32 v10, v72, v10, s43
	v_exp_f32_e32 v37, v37
	v_sub_f32_e32 v73, v73, v67
	ds_write_b16_d16_hi v87, v10 offset:128
	v_bfe_u32 v10, v122, 16, 1
	v_mul_f32_e32 v73, 0x3fb8aa3b, v73
	v_add3_u32 v10, v122, v10, s43
	v_exp_f32_e32 v73, v73
	v_sub_f32_e32 v26, v105, v97
	ds_write_b16_d16_hi v87, v10 offset:464
	v_bfe_u32 v10, v131, 16, 1
	v_mul_f32_e32 v26, 0x3fb8aa3b, v26
	v_add3_u32 v10, v131, v10, s43
	v_exp_f32_e32 v123, v26
	ds_write_b16_d16_hi v87, v10 offset:800
	v_bfe_u32 v10, v37, 16, 1
	v_add3_u32 v10, v37, v10, s43
	v_fma_f32 v16, v16, s42, -v13
	ds_write_b16_d16_hi v86, v10 offset:160
	v_bfe_u32 v10, v73, 16, 1
	v_mul_f32_e32 v16, 0x3fb8aa3b, v16
	v_add3_u32 v10, v73, v10, s43
	v_exp_f32_e32 v109, v16
	v_fma_f32 v17, v17, s42, -v67
	ds_write_b16_d16_hi v87, v10 offset:160
	v_bfe_u32 v10, v123, 16, 1
	v_mul_f32_e32 v17, 0x3fb8aa3b, v17
	v_add3_u32 v10, v123, v10, s43
	v_exp_f32_e32 v17, v17
	v_fma_f32 v18, v18, s42, -v97
	ds_write_b16_d16_hi v87, v10 offset:496
	v_bfe_u32 v10, v132, 16, 1
	v_mul_f32_e32 v18, 0x3fb8aa3b, v18
	v_add3_u32 v10, v132, v10, s43
	v_exp_f32_e32 v125, v18
	ds_write_b16_d16_hi v87, v10 offset:832
	v_bfe_u32 v10, v109, 16, 1
	v_add3_u32 v10, v109, v10, s43
	v_fma_f32 v16, v20, s42, -v13
	ds_write_b16_d16_hi v86, v10 offset:192
	v_bfe_u32 v10, v17, 16, 1
	v_add_f32_e32 v106, 0, v12
	v_mul_f32_e32 v16, 0x3fb8aa3b, v16
	v_add3_u32 v10, v17, v10, s43
	v_add_f32_e32 v106, v14, v106
	v_exp_f32_e32 v20, v16
	v_fma_f32 v21, v21, s42, -v67
	ds_write_b16_d16_hi v87, v10 offset:192
	v_bfe_u32 v10, v125, 16, 1
	v_add_f32_e32 v106, v15, v106
	v_sub_f32_e32 v8, v8, v13
	v_mul_f32_e32 v21, 0x3fb8aa3b, v21
	v_add3_u32 v10, v125, v10, s43
	v_add_f32_e32 v106, v24, v106
	v_mul_f32_e32 v8, 0x3fb8aa3b, v8
	v_exp_f32_e32 v21, v21
	v_fma_f32 v18, v22, s42, -v97
	ds_write_b16_d16_hi v87, v10 offset:528
	v_bfe_u32 v10, v133, 16, 1
	v_add_f32_e32 v106, v28, v106
	v_exp_f32_e32 v8, v8
	v_mul_f32_e32 v18, 0x3fb8aa3b, v18
	v_add3_u32 v10, v133, v10, s43
	v_add_f32_e32 v16, v37, v106
	v_exp_f32_e32 v126, v18
	ds_write_b16_d16_hi v87, v10 offset:864
	v_bfe_u32 v10, v20, 16, 1
	v_add_f32_e32 v16, v109, v16
	v_add3_u32 v10, v20, v10, s43
	v_add_f32_e32 v16, v20, v16
	v_sub_f32_e32 v13, v35, v13
	ds_write_b16_d16_hi v86, v10 offset:224
	v_bfe_u32 v10, v21, 16, 1
	v_add_f32_e32 v16, v8, v16
	v_mul_f32_e32 v13, 0x3fb8aa3b, v13
	v_add3_u32 v10, v21, v10, s43
	v_add_f32_dpp v16, v16, v16 quad_perm:[1,0,3,2] row_mask:0xf bank_mask:0xf bound_ctrl:1
	v_exp_f32_e32 v13, v13
	v_sub_f32_e32 v9, v9, v67
	ds_write_b16_d16_hi v87, v10 offset:224
	v_bfe_u32 v10, v126, 16, 1
	v_add_f32_dpp v16, v16, v16 quad_perm:[2,3,0,1] row_mask:0xf bank_mask:0xf bound_ctrl:1
	v_mul_f32_e32 v9, 0x3fb8aa3b, v9
	v_add3_u32 v10, v126, v10, s43
	v_add_f32_dpp v16, v16, v16 row_ror:4 row_mask:0xf bank_mask:0xf bound_ctrl:1
	v_exp_f32_e32 v9, v9
	ds_write_b16_d16_hi v87, v10 offset:560
	v_bfe_u32 v10, v134, 16, 1
	v_add_f32_dpp v16, v16, v16 row_ror:8 row_mask:0xf bank_mask:0xf bound_ctrl:1
	v_add3_u32 v10, v134, v10, s43
	v_add_f32_e32 v16, v13, v16
	v_add_f32_e32 v13, 0, v25
	ds_write_b16_d16_hi v87, v10 offset:896
	v_bfe_u32 v10, v8, 16, 1
	v_add_f32_e32 v13, v29, v13
	v_add3_u32 v8, v8, v10, s43
	v_add_f32_e32 v13, v68, v13
	ds_write_b16_d16_hi v86, v8 offset:256
	v_bfe_u32 v8, v9, 16, 1
	v_add_f32_e32 v13, v69, v13
	v_add3_u32 v8, v9, v8, s43
	v_add_f32_e32 v13, v72, v13
	ds_write_b16_d16_hi v87, v8 offset:256
	v_bfe_u32 v8, v127, 16, 1
	v_add_f32_e32 v13, v73, v13
	v_add3_u32 v8, v127, v8, s43
	v_add_f32_e32 v13, v17, v13
	ds_write_b16_d16_hi v87, v8 offset:592
	v_bfe_u32 v8, v135, 16, 1
	v_add_f32_e32 v13, v21, v13
	v_add3_u32 v8, v135, v8, s43
	v_add_f32_e32 v13, v9, v13
	ds_write_b16_d16_hi v87, v8 offset:928
	ds_read_b128 v[8:11], v88
	v_add_f32_dpp v13, v13, v13 quad_perm:[1,0,3,2] row_mask:0xf bank_mask:0xf bound_ctrl:1
	v_sub_f32_e32 v18, v35, v67
	v_mul_f32_e32 v37, 0x3fb8aa3b, v18
	v_add_f32_dpp v13, v13, v13 quad_perm:[2,3,0,1] row_mask:0xf bank_mask:0xf bound_ctrl:1
	v_exp_f32_e32 v37, v37
	s_nop 0
	v_add_f32_dpp v12, v13, v13 row_ror:4 row_mask:0xf bank_mask:0xf bound_ctrl:1
	s_nop 1
	v_add_f32_dpp v17, v12, v12 row_ror:8 row_mask:0xf bank_mask:0xf bound_ctrl:1
	ds_read_b128 v[12:15], v93 offset:36864
	ds_read_b128 v[18:21], v93 offset:45824
	ds_read_b128 v[22:25], v88 offset:64
	ds_read_b128 v[26:29], v88 offset:256
	s_waitcnt lgkmcnt(3)
	v_mfma_f32_16x16x32_bf16 v[12:15], v[8:11], v[12:15], 0
	ds_read_b128 v[68:71], v93 offset:54784
	ds_read_b128 v[72:75], v93 offset:45888
	v_add_f32_e32 v17, v37, v17
	ds_read_b128 v[104:107], v93 offset:63744
	ds_read_b128 v[108:111], v93 offset:46080
	v_add_f32_e32 v37, 0, v112
	ds_read_b128 v[112:115], v93 offset:36928
	ds_read_b128 v[116:119], v93 offset:63808
	s_waitcnt lgkmcnt(8)
	v_mfma_f32_16x16x32_bf16 v[18:21], v[8:11], v[18:21], 0
	v_add_f32_e32 v30, v30, v37
	v_add_f32_e32 v30, v120, v30
	v_add_f32_e32 v30, v121, v30
	s_waitcnt lgkmcnt(5)
	v_mfma_f32_16x16x32_bf16 v[68:71], v[8:11], v[68:71], 0
	v_add_f32_e32 v30, v122, v30
	v_add_f32_e32 v30, v123, v30
	v_add_f32_e32 v30, v125, v30
	s_waitcnt lgkmcnt(3)
	v_mfma_f32_16x16x32_bf16 v[8:11], v[8:11], v[104:107], 0
	ds_read_b128 v[104:107], v93 offset:36992
	v_add_f32_e32 v30, v126, v30
	v_add_f32_e32 v30, v127, v30
	s_waitcnt lgkmcnt(2)
	v_mfma_f32_16x16x32_bf16 v[12:15], v[22:25], v[112:115], v[12:15]
	ds_read_b128 v[112:115], v93 offset:54848
	v_add_f32_dpp v30, v30, v30 quad_perm:[1,0,3,2] row_mask:0xf bank_mask:0xf bound_ctrl:1
	v_mfma_f32_16x16x32_bf16 v[18:21], v[22:25], v[72:75], v[18:21]
	ds_read_b128 v[72:75], v88 offset:128
	ds_read_b128 v[120:123], v93 offset:54912
	v_add_f32_dpp v30, v30, v30 quad_perm:[2,3,0,1] row_mask:0xf bank_mask:0xf bound_ctrl:1
	s_waitcnt lgkmcnt(2)
	v_mfma_f32_16x16x32_bf16 v[68:71], v[22:25], v[112:115], v[68:71]
	v_add_f32_dpp v30, v30, v30 row_ror:4 row_mask:0xf bank_mask:0xf bound_ctrl:1
	v_mfma_f32_16x16x32_bf16 v[8:11], v[22:25], v[116:119], v[8:11]
	ds_read_b128 v[22:25], v93 offset:45952
	ds_read_b128 v[112:115], v88 offset:192
	s_waitcnt lgkmcnt(1)
	v_mfma_f32_16x16x32_bf16 v[18:21], v[72:75], v[22:25], v[18:21]
	v_sub_f32_e32 v22, v35, v97
	v_mul_f32_e32 v37, 0x3fb8aa3b, v22
	ds_read_b128 v[22:25], v93 offset:63872
	v_mfma_f32_16x16x32_bf16 v[12:15], v[72:75], v[104:107], v[12:15]
	ds_read_b128 v[104:107], v93 offset:46016
	v_exp_f32_e32 v37, v37
	s_waitcnt lgkmcnt(1)
	v_mfma_f32_16x16x32_bf16 v[8:11], v[72:75], v[22:25], v[8:11]
	v_add_f32_dpp v22, v30, v30 row_ror:8 row_mask:0xf bank_mask:0xf bound_ctrl:1
	v_add_f32_e32 v30, v37, v22
	v_add_f32_e32 v37, 0, v128
	v_add_f32_e32 v31, v31, v37
	v_mfma_f32_16x16x32_bf16 v[68:71], v[72:75], v[120:123], v[68:71]
	ds_read_b128 v[116:119], v93 offset:37056
	ds_read_b128 v[120:123], v93 offset:63936
	v_add_f32_e32 v31, v129, v31
	v_add_f32_e32 v31, v130, v31
	v_add_f32_e32 v31, v131, v31
	ds_read_b128 v[22:25], v93 offset:37120
	ds_read_b128 v[72:75], v93 offset:54976
	v_add_f32_e32 v31, v132, v31
	s_waitcnt lgkmcnt(3)
	v_mfma_f32_16x16x32_bf16 v[12:15], v[112:115], v[116:119], v[12:15]
	v_add_f32_e32 v31, v133, v31
	v_add_f32_e32 v31, v134, v31
	v_add_f32_e32 v31, v135, v31
	s_waitcnt lgkmcnt(1)
	v_mfma_f32_16x16x32_bf16 v[22:25], v[26:29], v[22:25], v[12:15]
	v_add_f32_dpp v31, v31, v31 quad_perm:[1,0,3,2] row_mask:0xf bank_mask:0xf bound_ctrl:1
	v_mfma_f32_16x16x32_bf16 v[18:21], v[112:115], v[104:107], v[18:21]
	s_nop 0
	v_add_f32_dpp v12, v31, v31 quad_perm:[2,3,0,1] row_mask:0xf bank_mask:0xf bound_ctrl:1
	ds_read_b128 v[104:107], v93 offset:55040
	s_nop 2
	v_add_f32_dpp v12, v12, v12 row_ror:4 row_mask:0xf bank_mask:0xf bound_ctrl:1
	s_waitcnt lgkmcnt(1)
	v_mfma_f32_16x16x32_bf16 v[68:71], v[112:115], v[72:75], v[68:71]
	v_add_f32_dpp v31, v12, v12 row_ror:8 row_mask:0xf bank_mask:0xf bound_ctrl:1
	v_sub_f32_e32 v12, v35, v124
	v_mul_f32_e32 v12, 0x3fb8aa3b, v12
	v_exp_f32_e32 v37, v12
	ds_read_b128 v[12:15], v93 offset:64000
	v_mfma_f32_16x16x32_bf16 v[8:11], v[112:115], v[120:123], v[8:11]
	v_add_f32_e32 v31, v37, v31
	s_waitcnt lgkmcnt(0)
	v_mfma_f32_16x16x32_bf16 v[8:11], v[26:29], v[12:15], v[8:11]
	v_or_b32_e32 v12, v34, v62
	v_mad_u64_u32 v[12:13], s[34:35], v12, s44, v[32:33]
	v_add_u32_e32 v13, s10, v13
	v_mfma_f32_16x16x32_bf16 v[18:21], v[26:29], v[108:111], v[18:21]
	v_mfma_f32_16x16x32_bf16 v[68:71], v[26:29], v[104:107], v[68:71]
	v_add_co_u32_e32 v14, vcc, 0x1000, v12
	s_nop 1
	v_addc_co_u32_e32 v15, vcc, 0, v13, vcc
	v_rcp_f32_e32 v194, v16
	v_rcp_f32_e32 v195, v17
	v_rcp_f32_e32 v196, v30
	v_rcp_f32_e32 v197, v31
	s_nop 0
	v_fma_f32 v240, -v16, v194, 1.0
	v_fma_f32 v241, -v17, v195, 1.0
	v_fma_f32 v242, -v30, v196, 1.0
	v_fma_f32 v243, -v31, v197, 1.0
	v_fmac_f32_e32 v194, v240, v194
	v_fmac_f32_e32 v195, v241, v195
	v_fmac_f32_e32 v196, v242, v196
	v_fmac_f32_e32 v197, v243, v197
	v_fma_f32 v240, -v16, v194, 1.0
	v_fma_f32 v241, -v17, v195, 1.0
	v_fma_f32 v242, -v30, v196, 1.0
	v_fma_f32 v243, -v31, v197, 1.0
	v_fmac_f32_e32 v194, v240, v194
	v_fmac_f32_e32 v195, v241, v195
	v_fmac_f32_e32 v196, v242, v196
	v_fmac_f32_e32 v197, v243, v197
	v_mul_f32_e32 v198, v22, v194
	v_mul_f32_e32 v199, v23, v195
	v_mul_f32_e32 v200, v24, v196
	v_mul_f32_e32 v201, v25, v197
	v_mul_f32_e32 v202, v18, v194
	v_mul_f32_e32 v203, v19, v195
	v_mul_f32_e32 v204, v20, v196
	v_mul_f32_e32 v205, v21, v197
	v_mul_f32_e32 v206, v68, v194
	v_mul_f32_e32 v207, v69, v195
	v_mul_f32_e32 v208, v70, v196
	v_mul_f32_e32 v209, v71, v197
	v_mul_f32_e32 v210, v8, v194
	v_mul_f32_e32 v211, v9, v195
	v_mul_f32_e32 v212, v10, v196
	v_mul_f32_e32 v213, v11, v197
	v_and_b32_e32 v240, 3, v174
	v_mul_u32_u24_e32 v240, 0x87e, v240
	v_mov_b32_e32 v241, 0
	v_lshl_add_u64 v[238:239], v[12:13], 0, v[240:241]
	s_mov_b32 vcc_lo, 0x55555555
	s_mov_b32 vcc_hi, 0x55555555
	s_nop 1
	v_cndmask_b32_dpp v214, v199, v198, vcc quad_perm:[1,0,3,2] row_mask:0xf bank_mask:0xf
	v_cndmask_b32_dpp v216, v201, v200, vcc quad_perm:[1,0,3,2] row_mask:0xf bank_mask:0xf
	v_cndmask_b32_dpp v218, v203, v202, vcc quad_perm:[1,0,3,2] row_mask:0xf bank_mask:0xf
	v_cndmask_b32_dpp v220, v205, v204, vcc quad_perm:[1,0,3,2] row_mask:0xf bank_mask:0xf
	v_cndmask_b32_dpp v222, v207, v206, vcc quad_perm:[1,0,3,2] row_mask:0xf bank_mask:0xf
	v_cndmask_b32_dpp v224, v209, v208, vcc quad_perm:[1,0,3,2] row_mask:0xf bank_mask:0xf
	v_cndmask_b32_dpp v226, v211, v210, vcc quad_perm:[1,0,3,2] row_mask:0xf bank_mask:0xf
	v_cndmask_b32_dpp v228, v213, v212, vcc quad_perm:[1,0,3,2] row_mask:0xf bank_mask:0xf
	s_mov_b32 vcc_lo, 0xaaaaaaaa
	s_mov_b32 vcc_hi, 0xaaaaaaaa
	s_nop 1
	v_cndmask_b32_dpp v215, v198, v199, vcc quad_perm:[1,0,3,2] row_mask:0xf bank_mask:0xf
	v_cndmask_b32_dpp v217, v200, v201, vcc quad_perm:[1,0,3,2] row_mask:0xf bank_mask:0xf
	v_cndmask_b32_dpp v219, v202, v203, vcc quad_perm:[1,0,3,2] row_mask:0xf bank_mask:0xf
	v_cndmask_b32_dpp v221, v204, v205, vcc quad_perm:[1,0,3,2] row_mask:0xf bank_mask:0xf
	v_cndmask_b32_dpp v223, v206, v207, vcc quad_perm:[1,0,3,2] row_mask:0xf bank_mask:0xf
	v_cndmask_b32_dpp v225, v208, v209, vcc quad_perm:[1,0,3,2] row_mask:0xf bank_mask:0xf
	v_cndmask_b32_dpp v227, v210, v211, vcc quad_perm:[1,0,3,2] row_mask:0xf bank_mask:0xf
	v_cndmask_b32_dpp v229, v212, v213, vcc quad_perm:[1,0,3,2] row_mask:0xf bank_mask:0xf
	s_mov_b32 vcc_lo, 0x33333333
	s_mov_b32 vcc_hi, 0x33333333
	s_nop 1
	v_cndmask_b32_dpp v198, v216, v214, vcc quad_perm:[2,3,0,1] row_mask:0xf bank_mask:0xf
	v_cndmask_b32_dpp v199, v217, v215, vcc quad_perm:[2,3,0,1] row_mask:0xf bank_mask:0xf
	v_cndmask_b32_dpp v202, v220, v218, vcc quad_perm:[2,3,0,1] row_mask:0xf bank_mask:0xf
	v_cndmask_b32_dpp v203, v221, v219, vcc quad_perm:[2,3,0,1] row_mask:0xf bank_mask:0xf
	v_cndmask_b32_dpp v206, v224, v222, vcc quad_perm:[2,3,0,1] row_mask:0xf bank_mask:0xf
	v_cndmask_b32_dpp v207, v225, v223, vcc quad_perm:[2,3,0,1] row_mask:0xf bank_mask:0xf
	v_cndmask_b32_dpp v210, v228, v226, vcc quad_perm:[2,3,0,1] row_mask:0xf bank_mask:0xf
	v_cndmask_b32_dpp v211, v229, v227, vcc quad_perm:[2,3,0,1] row_mask:0xf bank_mask:0xf
	s_mov_b32 vcc_lo, 0xcccccccc
	s_mov_b32 vcc_hi, 0xcccccccc
	s_nop 1
	v_cndmask_b32_dpp v200, v214, v216, vcc quad_perm:[2,3,0,1] row_mask:0xf bank_mask:0xf
	v_cndmask_b32_dpp v201, v215, v217, vcc quad_perm:[2,3,0,1] row_mask:0xf bank_mask:0xf
	v_cndmask_b32_dpp v204, v218, v220, vcc quad_perm:[2,3,0,1] row_mask:0xf bank_mask:0xf
	v_cndmask_b32_dpp v205, v219, v221, vcc quad_perm:[2,3,0,1] row_mask:0xf bank_mask:0xf
	v_cndmask_b32_dpp v208, v222, v224, vcc quad_perm:[2,3,0,1] row_mask:0xf bank_mask:0xf
	v_cndmask_b32_dpp v209, v223, v225, vcc quad_perm:[2,3,0,1] row_mask:0xf bank_mask:0xf
	v_cndmask_b32_dpp v212, v226, v228, vcc quad_perm:[2,3,0,1] row_mask:0xf bank_mask:0xf
	v_cndmask_b32_dpp v213, v227, v229, vcc quad_perm:[2,3,0,1] row_mask:0xf bank_mask:0xf
	v_cvt_pk_bf16_f32 v230, v198, v199
	v_cvt_pk_bf16_f32 v231, v200, v201
	v_cvt_pk_bf16_f32 v232, v202, v203
	v_cvt_pk_bf16_f32 v233, v204, v205
	v_cvt_pk_bf16_f32 v234, v206, v207
	v_cvt_pk_bf16_f32 v235, v208, v209
	v_cvt_pk_bf16_f32 v236, v210, v211
	v_cvt_pk_bf16_f32 v237, v212, v213
	global_store_dwordx2 v[238:239], v[230:231], off offset:0
	global_store_dwordx2 v[238:239], v[232:233], off offset:32
	global_store_dwordx2 v[238:239], v[234:235], off offset:64
	global_store_dwordx2 v[238:239], v[236:237], off offset:96
	ds_read_b128 v[8:11], v94
	ds_read_b128 v[12:15], v94 offset:64
	s_waitcnt lgkmcnt(1)
	v_mfma_f32_16x16x32_bf16 v[8:11], v[0:3], v[8:11], 0
	s_waitcnt lgkmcnt(0)
	v_mfma_f32_16x16x32_bf16 v[20:23], v[4:7], v[12:15], v[8:11]
	s_nop 5
	ds_read_b128 v[8:11], v94 offset:2304
	ds_read_b128 v[12:15], v94 offset:2368
	v_mul_f32_e32 v21, 0x3e000000, v21
	s_waitcnt lgkmcnt(1)
	v_mfma_f32_16x16x32_bf16 v[8:11], v[0:3], v[8:11], 0
	v_cndmask_b32_e64 v21, v96, v21, s[26:27]
	v_mul_f32_e32 v22, 0x3e000000, v22
	v_cndmask_b32_e64 v22, v96, v22, s[28:29]
	s_waitcnt lgkmcnt(0)
	v_mfma_f32_16x16x32_bf16 v[24:27], v[4:7], v[12:15], v[8:11]
	s_nop 2
	ds_read_b128 v[8:11], v94 offset:4608
	ds_read_b128 v[12:15], v94 offset:4672
	v_mul_f32_e32 v23, 0x3e000000, v23
	v_cndmask_b32_e64 v23, v96, v23, s[30:31]
	s_waitcnt lgkmcnt(1)
	v_mfma_f32_16x16x32_bf16 v[8:11], v[0:3], v[8:11], 0
	v_mul_f32_e32 v25, 0x3e000000, v25
	v_cndmask_b32_e64 v25, v96, v25, s[22:23]
	v_mul_f32_e32 v26, 0x3e000000, v26
	s_waitcnt lgkmcnt(0)
	v_mfma_f32_16x16x32_bf16 v[28:31], v[4:7], v[12:15], v[8:11]
	s_nop 2
	ds_read_b128 v[8:11], v94 offset:6912
	ds_read_b128 v[12:15], v94 offset:6976
	v_cndmask_b32_e64 v26, v96, v26, s[22:23]
	v_mul_f32_e32 v27, 0x3e000000, v27
	s_waitcnt lgkmcnt(1)
	v_mfma_f32_16x16x32_bf16 v[8:11], v[0:3], v[8:11], 0
	v_mul_f32_e32 v29, 0x3e000000, v29
	v_cndmask_b32_e64 v29, v96, v29, s[22:23]
	v_mul_f32_e32 v30, 0x3e000000, v30
	s_waitcnt lgkmcnt(0)
	v_mfma_f32_16x16x32_bf16 v[68:71], v[4:7], v[12:15], v[8:11]
	s_nop 2
	ds_read_b128 v[8:11], v94 offset:9216
	ds_read_b128 v[12:15], v94 offset:9280
	v_cndmask_b32_e64 v30, v96, v30, s[22:23]
	v_mul_f32_e32 v31, 0x3e000000, v31
	s_waitcnt lgkmcnt(1)
	v_mfma_f32_16x16x32_bf16 v[8:11], v[0:3], v[8:11], 0
	v_cndmask_b32_e64 v27, v96, v27, s[22:23]
	v_cndmask_b32_e64 v31, v96, v31, s[22:23]
	s_waitcnt lgkmcnt(0)
	v_mfma_f32_16x16x32_bf16 v[72:75], v[4:7], v[12:15], v[8:11]
	s_nop 3
	ds_read_b128 v[8:11], v94 offset:11520
	ds_read_b128 v[12:15], v94 offset:11584
	s_nop 1
	v_mul_f32_e32 v67, 0x3e000000, v73
	s_waitcnt lgkmcnt(1)
	v_mfma_f32_16x16x32_bf16 v[8:11], v[0:3], v[8:11], 0
	v_cndmask_b32_e64 v67, v96, v67, s[22:23]
	s_waitcnt lgkmcnt(0)
	v_mfma_f32_16x16x32_bf16 v[8:11], v[4:7], v[12:15], v[8:11]
	ds_read_b128 v[12:15], v94 offset:13824
	ds_read_b128 v[16:19], v94 offset:13888
	s_waitcnt lgkmcnt(1)
	v_mfma_f32_16x16x32_bf16 v[12:15], v[0:3], v[12:15], 0
	s_waitcnt lgkmcnt(0)
	v_mfma_f32_16x16x32_bf16 v[12:15], v[4:7], v[16:19], v[12:15]
	ds_read_b128 v[16:19], v94 offset:16128
	ds_read_b128 v[104:107], v94 offset:16192
	s_waitcnt lgkmcnt(1)
	v_mfma_f32_16x16x32_bf16 v[16:19], v[0:3], v[16:19], 0
	s_nop 3
	v_mul_f32_e32 v37, 0x3e000000, v12
	v_mul_f32_e32 v73, 0x3e000000, v14
	s_waitcnt lgkmcnt(0)
	v_mfma_f32_16x16x32_bf16 v[16:19], v[4:7], v[104:107], v[16:19]
	ds_read_b128 v[104:107], v94 offset:18432
	ds_read_b128 v[108:111], v94 offset:18496
	s_waitcnt lgkmcnt(1)
	v_mfma_f32_16x16x32_bf16 v[0:3], v[0:3], v[104:107], 0
	s_waitcnt lgkmcnt(0)
	v_mfma_f32_16x16x32_bf16 v[0:3], v[4:7], v[108:111], v[0:3]
	v_mul_f32_e32 v4, 0x3e000000, v20
	v_cndmask_b32_e64 v4, v96, v4, s[24:25]
	v_mul_f32_e32 v6, 0x3e000000, v24
	v_mul_f32_e32 v7, 0x3e000000, v28
	v_max_f32_e32 v5, v36, v4
	v_cndmask_b32_e64 v6, v96, v6, s[22:23]
	v_cndmask_b32_e64 v7, v96, v7, s[22:23]
	v_mul_f32_e32 v20, 0x3e000000, v68
	v_mul_f32_e32 v24, 0x3e000000, v72
	v_max3_f32 v5, v5, v6, v7
	v_cndmask_b32_e64 v20, v96, v20, s[22:23]
	v_cndmask_b32_e64 v24, v96, v24, s[22:23]
	v_max3_f32 v5, v5, v20, v24
	v_mul_f32_e32 v28, 0x3e000000, v8
	v_mul_f32_e32 v0, 0x3e000000, v0
	v_max3_f32 v5, v5, v28, v37
	v_mul_f32_e32 v28, 0x3e000000, v16
	v_cndmask_b32_e64 v0, v0, v96, s[6:7]
	v_max3_f32 v5, v5, v28, v0
	v_mul_f32_e32 v37, 0x3e000000, v69
	v_cndmask_b32_e64 v37, v96, v37, s[22:23]
	v_mov_b32_dpp v28, v5 quad_perm:[1,0,3,2] row_mask:0xf bank_mask:0xf bound_ctrl:1
	v_max_f32_e32 v28, v28, v28
	v_max_f32_e32 v5, v5, v28
	v_mul_f32_e32 v68, 0x3e000000, v9
	v_mul_f32_e32 v69, 0x3e000000, v13
	v_mov_b32_dpp v28, v5 quad_perm:[2,3,0,1] row_mask:0xf bank_mask:0xf bound_ctrl:1
	v_max_f32_e32 v28, v28, v28
	v_max_f32_e32 v5, v5, v28
	v_mul_f32_e32 v1, 0x3e000000, v1
	v_cndmask_b32_e64 v1, v1, v96, s[12:13]
	v_mov_b32_dpp v28, v5 row_ror:4 row_mask:0xf bank_mask:0xf bound_ctrl:1
	v_max_f32_e32 v28, v28, v28
	v_max_f32_e32 v5, v5, v28
	v_mul_f32_e32 v72, 0x3e000000, v10
	v_mul_f32_e32 v2, 0x3e000000, v2
	v_mov_b32_dpp v28, v5 row_ror:8 row_mask:0xf bank_mask:0xf bound_ctrl:1
	v_max_f32_e32 v28, v28, v28
	v_max_f32_e32 v5, v5, v28
	v_max_f32_e32 v28, v36, v21
	v_max3_f32 v28, v28, v25, v29
	v_max3_f32 v28, v28, v37, v67
	v_max3_f32 v28, v28, v68, v69
	v_mul_f32_e32 v68, 0x3e000000, v17
	v_max3_f32 v28, v28, v68, v1
	v_mul_f32_e32 v69, 0x3e000000, v70
	v_mul_f32_e32 v70, 0x3e000000, v74
	v_mov_b32_dpp v68, v28 quad_perm:[1,0,3,2] row_mask:0xf bank_mask:0xf bound_ctrl:1
	v_max_f32_e32 v68, v68, v68
	v_max_f32_e32 v28, v28, v68
	v_cndmask_b32_e64 v69, v96, v69, s[22:23]
	v_cndmask_b32_e64 v70, v96, v70, s[22:23]
	v_mov_b32_dpp v68, v28 quad_perm:[2,3,0,1] row_mask:0xf bank_mask:0xf bound_ctrl:1
	v_max_f32_e32 v68, v68, v68
	v_max_f32_e32 v28, v28, v68
	v_cndmask_b32_e64 v2, v2, v96, s[16:17]
	v_mul_f32_e32 v3, 0x3e000000, v3
	v_mov_b32_dpp v68, v28 row_ror:4 row_mask:0xf bank_mask:0xf bound_ctrl:1
	v_max_f32_e32 v68, v68, v68
	v_max_f32_e32 v28, v28, v68
	v_cndmask_b32_e64 v3, v3, v96, s[20:21]
	v_sub_f32_e32 v4, v4, v5
	v_mov_b32_dpp v68, v28 row_ror:8 row_mask:0xf bank_mask:0xf bound_ctrl:1
	v_max_f32_e32 v68, v68, v68
	v_max_f32_e32 v28, v28, v68
	v_max_f32_e32 v68, v36, v22
	v_max3_f32 v68, v68, v26, v30
	v_max3_f32 v68, v68, v69, v70
	v_max3_f32 v68, v68, v72, v73
	v_mul_f32_e32 v72, 0x3e000000, v18
	v_max3_f32 v68, v68, v72, v2
	v_max_f32_e32 v36, v36, v23
	v_max3_f32 v36, v36, v27, v31
	v_mov_b32_dpp v72, v68 quad_perm:[1,0,3,2] row_mask:0xf bank_mask:0xf bound_ctrl:1
	v_max_f32_e32 v72, v72, v72
	v_max_f32_e32 v68, v68, v72
	v_mul_f32_e32 v73, 0x3e000000, v15
	v_mul_f32_e32 v4, 0x3fb8aa3b, v4
	v_mov_b32_dpp v72, v68 quad_perm:[2,3,0,1] row_mask:0xf bank_mask:0xf bound_ctrl:1
	v_max_f32_e32 v72, v72, v72
	v_max_f32_e32 v68, v68, v72
	v_exp_f32_e32 v4, v4
	v_sub_f32_e32 v21, v21, v28
	v_mov_b32_dpp v72, v68 row_ror:4 row_mask:0xf bank_mask:0xf bound_ctrl:1
	v_max_f32_e32 v72, v72, v72
	v_max_f32_e32 v68, v68, v72
	v_mul_f32_e32 v21, 0x3fb8aa3b, v21
	v_exp_f32_e32 v21, v21
	v_mov_b32_dpp v72, v68 row_ror:8 row_mask:0xf bank_mask:0xf bound_ctrl:1
	v_max_f32_e32 v72, v72, v72
	v_max_f32_e32 v97, v68, v72
	v_mul_f32_e32 v68, 0x3e000000, v71
	v_mul_f32_e32 v71, 0x3e000000, v75
	v_cndmask_b32_e64 v68, v96, v68, s[22:23]
	v_cndmask_b32_e64 v71, v96, v71, s[22:23]
	v_max3_f32 v36, v36, v68, v71
	v_mul_f32_e32 v72, 0x3e000000, v11
	v_max3_f32 v36, v36, v72, v73
	v_mul_f32_e32 v72, 0x3e000000, v19
	v_max3_f32 v36, v36, v72, v3
	v_sub_f32_e32 v2, v2, v97
	v_mul_f32_e32 v2, 0x3fb8aa3b, v2
	v_mov_b32_dpp v72, v36 quad_perm:[1,0,3,2] row_mask:0xf bank_mask:0xf bound_ctrl:1
	v_max_f32_e32 v72, v72, v72
	v_max_f32_e32 v36, v36, v72
	v_exp_f32_e32 v118, v2
	v_sub_f32_e32 v22, v22, v97
	v_mov_b32_dpp v72, v36 quad_perm:[2,3,0,1] row_mask:0xf bank_mask:0xf bound_ctrl:1
	v_max_f32_e32 v72, v72, v72
	v_max_f32_e32 v36, v36, v72
	v_mul_f32_e32 v22, 0x3fb8aa3b, v22
	v_exp_f32_e32 v104, v22
	v_mov_b32_dpp v72, v36 row_ror:4 row_mask:0xf bank_mask:0xf bound_ctrl:1
	v_max_f32_e32 v72, v72, v72
	v_max_f32_e32 v36, v36, v72
	v_sub_f32_e32 v6, v6, v5
	v_mul_f32_e32 v6, 0x3fb8aa3b, v6
	v_mov_b32_dpp v72, v36 row_ror:8 row_mask:0xf bank_mask:0xf bound_ctrl:1
	v_max_f32_e32 v72, v72, v72
	v_max_f32_e32 v36, v36, v72
	v_sub_f32_e32 v2, v23, v36
	v_mul_f32_e32 v2, 0x3fb8aa3b, v2
	v_exp_f32_e32 v119, v2
	v_sub_f32_e32 v2, v27, v36
	v_mul_f32_e32 v2, 0x3fb8aa3b, v2
	v_exp_f32_e32 v120, v2
	v_sub_f32_e32 v2, v31, v36
	v_mul_f32_e32 v2, 0x3fb8aa3b, v2
	v_exp_f32_e32 v31, v2
	v_sub_f32_e32 v2, v68, v36
	v_mul_f32_e32 v2, 0x3fb8aa3b, v2
	v_exp_f32_e32 v121, v2
	v_sub_f32_e32 v2, v71, v36
	v_mul_f32_e32 v2, 0x3fb8aa3b, v2
	v_exp_f32_e32 v122, v2
	v_fma_f32 v2, v11, s42, -v36
	v_mul_f32_e32 v2, 0x3fb8aa3b, v2
	v_exp_f32_e32 v123, v2
	v_fma_f32 v2, v15, s42, -v36
	v_mul_f32_e32 v2, 0x3fb8aa3b, v2
	v_exp_f32_e32 v124, v2
	v_fma_f32 v2, v19, s42, -v36
	v_mul_f32_e32 v2, 0x3fb8aa3b, v2
	v_exp_f32_e32 v125, v2
	v_sub_f32_e32 v2, v3, v36
	v_mul_f32_e32 v2, 0x3fb8aa3b, v2
	v_exp_f32_e32 v126, v2
	v_bfe_u32 v2, v4, 16, 1
	v_add3_u32 v2, v4, v2, s43
	ds_write_b16_d16_hi v86, v2
	v_bfe_u32 v2, v21, 16, 1
	v_add3_u32 v2, v21, v2, s43
	v_exp_f32_e32 v6, v6
	v_sub_f32_e32 v25, v25, v28
	ds_write_b16_d16_hi v87, v2
	v_bfe_u32 v2, v104, 16, 1
	v_mul_f32_e32 v25, 0x3fb8aa3b, v25
	v_add3_u32 v2, v104, v2, s43
	v_exp_f32_e32 v25, v25
	v_sub_f32_e32 v22, v26, v97
	ds_write_b16_d16_hi v87, v2 offset:336
	v_bfe_u32 v2, v119, 16, 1
	v_mul_f32_e32 v22, 0x3fb8aa3b, v22
	v_add3_u32 v2, v119, v2, s43
	v_exp_f32_e32 v112, v22
	ds_write_b16_d16_hi v87, v2 offset:672
	v_bfe_u32 v2, v6, 16, 1
	v_add3_u32 v2, v6, v2, s43
	v_sub_f32_e32 v7, v7, v5
	ds_write_b16_d16_hi v86, v2 offset:32
	v_bfe_u32 v2, v25, 16, 1
	v_mul_f32_e32 v7, 0x3fb8aa3b, v7
	v_add3_u32 v2, v25, v2, s43
	v_exp_f32_e32 v7, v7
	v_sub_f32_e32 v29, v29, v28
	ds_write_b16_d16_hi v87, v2 offset:32
	v_bfe_u32 v2, v112, 16, 1
	v_mul_f32_e32 v29, 0x3fb8aa3b, v29
	v_add3_u32 v2, v112, v2, s43
	v_exp_f32_e32 v29, v29
	v_sub_f32_e32 v22, v30, v97
	ds_write_b16_d16_hi v87, v2 offset:368
	v_bfe_u32 v2, v120, 16, 1
	v_mul_f32_e32 v22, 0x3fb8aa3b, v22
	v_add3_u32 v2, v120, v2, s43
	v_exp_f32_e32 v30, v22
	ds_write_b16_d16_hi v87, v2 offset:704
	v_bfe_u32 v2, v7, 16, 1
	v_add3_u32 v2, v7, v2, s43
	v_sub_f32_e32 v20, v20, v5
	ds_write_b16_d16_hi v86, v2 offset:64
	v_bfe_u32 v2, v29, 16, 1
	v_mul_f32_e32 v20, 0x3fb8aa3b, v20
	v_add3_u32 v2, v29, v2, s43
	v_exp_f32_e32 v20, v20
	v_sub_f32_e32 v37, v37, v28
	ds_write_b16_d16_hi v87, v2 offset:64
	v_bfe_u32 v2, v30, 16, 1
	v_mul_f32_e32 v37, 0x3fb8aa3b, v37
	v_add3_u32 v2, v30, v2, s43
	v_exp_f32_e32 v37, v37
	v_sub_f32_e32 v22, v69, v97
	ds_write_b16_d16_hi v87, v2 offset:400
	v_bfe_u32 v2, v31, 16, 1
	v_mul_f32_e32 v22, 0x3fb8aa3b, v22
	v_add3_u32 v2, v31, v2, s43
	v_exp_f32_e32 v113, v22
	ds_write_b16_d16_hi v87, v2 offset:736
	v_bfe_u32 v2, v20, 16, 1
	v_add3_u32 v2, v20, v2, s43
	v_sub_f32_e32 v24, v24, v5
	ds_write_b16_d16_hi v86, v2 offset:96
	v_bfe_u32 v2, v37, 16, 1
	v_mul_f32_e32 v24, 0x3fb8aa3b, v24
	v_add3_u32 v2, v37, v2, s43
	v_exp_f32_e32 v24, v24
	v_sub_f32_e32 v67, v67, v28
	ds_write_b16_d16_hi v87, v2 offset:96
	v_bfe_u32 v2, v113, 16, 1
	v_mul_f32_e32 v67, 0x3fb8aa3b, v67
	v_add3_u32 v2, v113, v2, s43
	v_exp_f32_e32 v67, v67
	v_sub_f32_e32 v22, v70, v97
	ds_write_b16_d16_hi v87, v2 offset:432
	v_bfe_u32 v2, v121, 16, 1
	v_mul_f32_e32 v22, 0x3fb8aa3b, v22
	v_add3_u32 v2, v121, v2, s43
	v_exp_f32_e32 v114, v22
	ds_write_b16_d16_hi v87, v2 offset:768
	v_bfe_u32 v2, v24, 16, 1
	v_add3_u32 v2, v24, v2, s43
	v_fma_f32 v8, v8, s42, -v5
	ds_write_b16_d16_hi v86, v2 offset:128
	v_bfe_u32 v2, v67, 16, 1
	v_mul_f32_e32 v8, 0x3fb8aa3b, v8
	v_add3_u32 v2, v67, v2, s43
	v_exp_f32_e32 v73, v8
	v_fma_f32 v9, v9, s42, -v28
	ds_write_b16_d16_hi v87, v2 offset:128
	v_bfe_u32 v2, v114, 16, 1
	v_mul_f32_e32 v9, 0x3fb8aa3b, v9
	v_add3_u32 v2, v114, v2, s43
	v_exp_f32_e32 v9, v9
	v_fma_f32 v10, v10, s42, -v97
	ds_write_b16_d16_hi v87, v2 offset:464
	v_bfe_u32 v2, v122, 16, 1
	v_mul_f32_e32 v10, 0x3fb8aa3b, v10
	v_add3_u32 v2, v122, v2, s43
	v_exp_f32_e32 v115, v10
	ds_write_b16_d16_hi v87, v2 offset:800
	v_bfe_u32 v2, v73, 16, 1
	v_add3_u32 v2, v73, v2, s43
	v_fma_f32 v8, v12, s42, -v5
	ds_write_b16_d16_hi v86, v2 offset:160
	v_bfe_u32 v2, v9, 16, 1
	v_mul_f32_e32 v8, 0x3fb8aa3b, v8
	v_add3_u32 v2, v9, v2, s43
	v_exp_f32_e32 v12, v8
	v_fma_f32 v13, v13, s42, -v28
	ds_write_b16_d16_hi v87, v2 offset:160
	v_bfe_u32 v2, v115, 16, 1
	v_mul_f32_e32 v13, 0x3fb8aa3b, v13
	v_add3_u32 v2, v115, v2, s43
	v_exp_f32_e32 v13, v13
	v_fma_f32 v10, v14, s42, -v97
	ds_write_b16_d16_hi v87, v2 offset:496
	v_bfe_u32 v2, v123, 16, 1
	v_mul_f32_e32 v10, 0x3fb8aa3b, v10
	v_add3_u32 v2, v123, v2, s43
	v_exp_f32_e32 v116, v10
	ds_write_b16_d16_hi v87, v2 offset:832
	v_bfe_u32 v2, v12, 16, 1
	v_add3_u32 v2, v12, v2, s43
	v_fma_f32 v8, v16, s42, -v5
	ds_write_b16_d16_hi v86, v2 offset:192
	v_bfe_u32 v2, v13, 16, 1
	v_add_f32_e32 v72, 0, v4
	v_mul_f32_e32 v8, 0x3fb8aa3b, v8
	v_add3_u32 v2, v13, v2, s43
	v_add_f32_e32 v72, v6, v72
	v_exp_f32_e32 v16, v8
	v_fma_f32 v17, v17, s42, -v28
	ds_write_b16_d16_hi v87, v2 offset:192
	v_bfe_u32 v2, v116, 16, 1
	v_add_f32_e32 v72, v7, v72
	v_sub_f32_e32 v0, v0, v5
	v_mul_f32_e32 v17, 0x3fb8aa3b, v17
	v_add3_u32 v2, v116, v2, s43
	v_add_f32_e32 v72, v20, v72
	v_mul_f32_e32 v0, 0x3fb8aa3b, v0
	v_exp_f32_e32 v17, v17
	v_fma_f32 v10, v18, s42, -v97
	ds_write_b16_d16_hi v87, v2 offset:528
	v_bfe_u32 v2, v124, 16, 1
	v_add_f32_e32 v72, v24, v72
	v_exp_f32_e32 v0, v0
	v_mul_f32_e32 v10, 0x3fb8aa3b, v10
	v_add3_u32 v2, v124, v2, s43
	v_add_f32_e32 v8, v73, v72
	v_exp_f32_e32 v117, v10
	ds_write_b16_d16_hi v87, v2 offset:864
	v_bfe_u32 v2, v16, 16, 1
	v_add_f32_e32 v8, v12, v8
	v_add3_u32 v2, v16, v2, s43
	v_add_f32_e32 v8, v16, v8
	v_sub_f32_e32 v5, v35, v5
	ds_write_b16_d16_hi v86, v2 offset:224
	v_bfe_u32 v2, v17, 16, 1
	v_add_f32_e32 v8, v0, v8
	v_mul_f32_e32 v5, 0x3fb8aa3b, v5
	v_add3_u32 v2, v17, v2, s43
	v_add_f32_dpp v8, v8, v8 quad_perm:[1,0,3,2] row_mask:0xf bank_mask:0xf bound_ctrl:1
	v_exp_f32_e32 v5, v5
	v_sub_f32_e32 v1, v1, v28
	ds_write_b16_d16_hi v87, v2 offset:224
	v_bfe_u32 v2, v117, 16, 1
	v_add_f32_dpp v8, v8, v8 quad_perm:[2,3,0,1] row_mask:0xf bank_mask:0xf bound_ctrl:1
	v_mul_f32_e32 v1, 0x3fb8aa3b, v1
	v_add3_u32 v2, v117, v2, s43
	v_add_f32_dpp v8, v8, v8 row_ror:4 row_mask:0xf bank_mask:0xf bound_ctrl:1
	v_exp_f32_e32 v1, v1
	ds_write_b16_d16_hi v87, v2 offset:560
	v_bfe_u32 v2, v125, 16, 1
	v_add_f32_dpp v8, v8, v8 row_ror:8 row_mask:0xf bank_mask:0xf bound_ctrl:1
	v_add3_u32 v2, v125, v2, s43
	v_add_f32_e32 v8, v5, v8
	v_add_f32_e32 v5, 0, v21
	ds_write_b16_d16_hi v87, v2 offset:896
	v_bfe_u32 v2, v0, 16, 1
	v_add_f32_e32 v5, v25, v5
	v_add3_u32 v0, v0, v2, s43
	v_add_f32_e32 v5, v29, v5
	ds_write_b16_d16_hi v86, v0 offset:256
	v_bfe_u32 v0, v1, 16, 1
	v_add_f32_e32 v5, v37, v5
	v_add3_u32 v0, v1, v0, s43
	v_add_f32_e32 v5, v67, v5
	ds_write_b16_d16_hi v87, v0 offset:256
	v_bfe_u32 v0, v118, 16, 1
	v_add_f32_e32 v5, v9, v5
	v_add3_u32 v0, v118, v0, s43
	v_add_f32_e32 v5, v13, v5
	ds_write_b16_d16_hi v87, v0 offset:592
	v_bfe_u32 v0, v126, 16, 1
	v_add_f32_e32 v5, v17, v5
	v_add3_u32 v0, v126, v0, s43
	v_add_f32_e32 v5, v1, v5
	ds_write_b16_d16_hi v87, v0 offset:928
	ds_read_b128 v[0:3], v88
	v_add_f32_dpp v5, v5, v5 quad_perm:[1,0,3,2] row_mask:0xf bank_mask:0xf bound_ctrl:1
	v_sub_f32_e32 v10, v35, v28
	v_mul_f32_e32 v22, 0x3fb8aa3b, v10
	v_add_f32_dpp v5, v5, v5 quad_perm:[2,3,0,1] row_mask:0xf bank_mask:0xf bound_ctrl:1
	v_exp_f32_e32 v37, v22
	s_nop 0
	v_add_f32_dpp v4, v5, v5 row_ror:4 row_mask:0xf bank_mask:0xf bound_ctrl:1
	s_nop 1
	v_add_f32_dpp v9, v4, v4 row_ror:8 row_mask:0xf bank_mask:0xf bound_ctrl:1
	ds_read_b128 v[4:7], v95 offset:36864
	ds_read_b128 v[10:13], v95 offset:45824
	ds_read_b128 v[14:17], v88 offset:64
	ds_read_b128 v[18:21], v88 offset:256
	s_waitcnt lgkmcnt(3)
	v_mfma_f32_16x16x32_bf16 v[4:7], v[0:3], v[4:7], 0
	ds_read_b128 v[22:25], v95 offset:54784
	ds_read_b128 v[26:29], v95 offset:45888
	v_add_f32_e32 v9, v37, v9
	ds_read_b128 v[68:71], v95 offset:63744
	ds_read_b128 v[72:75], v95 offset:46080
	v_add_f32_e32 v37, 0, v104
	ds_read_b128 v[104:107], v95 offset:36928
	ds_read_b128 v[108:111], v95 offset:63808
	s_waitcnt lgkmcnt(8)
	v_mfma_f32_16x16x32_bf16 v[10:13], v[0:3], v[10:13], 0
	v_add_f32_e32 v37, v112, v37
	v_add_f32_e32 v30, v30, v37
	v_add_f32_e32 v30, v113, v30
	s_waitcnt lgkmcnt(5)
	v_mfma_f32_16x16x32_bf16 v[22:25], v[0:3], v[22:25], 0
	v_add_f32_e32 v30, v114, v30
	v_add_f32_e32 v30, v115, v30
	v_add_f32_e32 v30, v116, v30
	s_waitcnt lgkmcnt(3)
	v_mfma_f32_16x16x32_bf16 v[0:3], v[0:3], v[68:71], 0
	ds_read_b128 v[68:71], v95 offset:36992
	v_add_f32_e32 v30, v117, v30
	v_add_f32_e32 v30, v118, v30
	s_waitcnt lgkmcnt(2)
	v_mfma_f32_16x16x32_bf16 v[4:7], v[14:17], v[104:107], v[4:7]
	ds_read_b128 v[104:107], v95 offset:54848
	v_add_f32_dpp v30, v30, v30 quad_perm:[1,0,3,2] row_mask:0xf bank_mask:0xf bound_ctrl:1
	v_mfma_f32_16x16x32_bf16 v[10:13], v[14:17], v[26:29], v[10:13]
	ds_read_b128 v[26:29], v88 offset:128
	ds_read_b128 v[112:115], v95 offset:54912
	v_add_f32_dpp v30, v30, v30 quad_perm:[2,3,0,1] row_mask:0xf bank_mask:0xf bound_ctrl:1
	s_waitcnt lgkmcnt(2)
	v_mfma_f32_16x16x32_bf16 v[22:25], v[14:17], v[104:107], v[22:25]
	v_add_f32_dpp v30, v30, v30 row_ror:4 row_mask:0xf bank_mask:0xf bound_ctrl:1
	v_mfma_f32_16x16x32_bf16 v[0:3], v[14:17], v[108:111], v[0:3]
	ds_read_b128 v[14:17], v95 offset:45952
	ds_read_b128 v[104:107], v88 offset:192
	s_waitcnt lgkmcnt(1)
	v_mfma_f32_16x16x32_bf16 v[10:13], v[26:29], v[14:17], v[10:13]
	v_sub_f32_e32 v14, v35, v97
	v_mul_f32_e32 v37, 0x3fb8aa3b, v14
	ds_read_b128 v[14:17], v95 offset:63872
	v_mfma_f32_16x16x32_bf16 v[4:7], v[26:29], v[68:71], v[4:7]
	ds_read_b128 v[68:71], v95 offset:46016
	v_exp_f32_e32 v37, v37
	v_mfma_f32_16x16x32_bf16 v[22:25], v[26:29], v[112:115], v[22:25]
	ds_read_b128 v[108:111], v95 offset:37056
	ds_read_b128 v[112:115], v95 offset:63936
	s_waitcnt lgkmcnt(3)
	v_mfma_f32_16x16x32_bf16 v[0:3], v[26:29], v[14:17], v[0:3]
	v_add_f32_dpp v14, v30, v30 row_ror:8 row_mask:0xf bank_mask:0xf bound_ctrl:1
	v_add_f32_e32 v26, 0, v119
	v_add_f32_e32 v30, v37, v14
	ds_read_b128 v[14:17], v95 offset:37120
	v_add_f32_e32 v37, v120, v26
	ds_read_b128 v[26:29], v95 offset:54976
	v_add_f32_e32 v31, v31, v37
	v_add_f32_e32 v31, v121, v31
	s_waitcnt lgkmcnt(0)
	v_mfma_f32_16x16x32_bf16 v[22:25], v[104:107], v[26:29], v[22:25]
	v_add_f32_e32 v26, v122, v31
	v_add_f32_e32 v26, v123, v26
	v_add_f32_e32 v26, v124, v26
	v_mfma_f32_16x16x32_bf16 v[4:7], v[104:107], v[108:111], v[4:7]
	v_add_f32_e32 v26, v125, v26
	v_add_f32_e32 v26, v126, v26
	v_mfma_f32_16x16x32_bf16 v[14:17], v[18:21], v[14:17], v[4:7]
	s_nop 0
	v_add_f32_dpp v26, v26, v26 quad_perm:[1,0,3,2] row_mask:0xf bank_mask:0xf bound_ctrl:1
	s_nop 2
	v_add_f32_dpp v4, v26, v26 quad_perm:[2,3,0,1] row_mask:0xf bank_mask:0xf bound_ctrl:1
	v_mfma_f32_16x16x32_bf16 v[10:13], v[104:107], v[68:71], v[10:13]
	ds_read_b128 v[68:71], v95 offset:55040
	v_add_f32_dpp v4, v4, v4 row_ror:4 row_mask:0xf bank_mask:0xf bound_ctrl:1
	s_nop 0
	v_add_f32_dpp v26, v4, v4 row_ror:8 row_mask:0xf bank_mask:0xf bound_ctrl:1
	v_sub_f32_e32 v4, v35, v36
	v_mul_f32_e32 v4, 0x3fb8aa3b, v4
	v_exp_f32_e32 v27, v4
	ds_read_b128 v[4:7], v95 offset:64000
	v_mfma_f32_16x16x32_bf16 v[0:3], v[104:107], v[112:115], v[0:3]
	v_add_f32_e32 v26, v27, v26
	s_waitcnt lgkmcnt(0)
	v_mfma_f32_16x16x32_bf16 v[0:3], v[18:21], v[4:7], v[0:3]
	v_mfma_f32_16x16x32_bf16 v[10:13], v[18:21], v[72:75], v[10:13]
	v_or_b32_e32 v4, v34, v64
	v_mfma_f32_16x16x32_bf16 v[22:25], v[18:21], v[68:71], v[22:25]
	v_mad_u64_u32 v[6:7], s[22:23], v4, s44, v[32:33]
	v_add_u32_e32 v7, s10, v7
	v_add_co_u32_e32 v4, vcc, 0x1000, v6
	s_nop 1
	v_addc_co_u32_e32 v5, vcc, 0, v7, vcc
	v_rcp_f32_e32 v194, v8
	v_rcp_f32_e32 v195, v9
	v_rcp_f32_e32 v196, v30
	v_rcp_f32_e32 v197, v26
	s_nop 0
	v_fma_f32 v240, -v8, v194, 1.0
	v_fma_f32 v241, -v9, v195, 1.0
	v_fma_f32 v242, -v30, v196, 1.0
	v_fma_f32 v243, -v26, v197, 1.0
	v_fmac_f32_e32 v194, v240, v194
	v_fmac_f32_e32 v195, v241, v195
	v_fmac_f32_e32 v196, v242, v196
	v_fmac_f32_e32 v197, v243, v197
	v_fma_f32 v240, -v8, v194, 1.0
	v_fma_f32 v241, -v9, v195, 1.0
	v_fma_f32 v242, -v30, v196, 1.0
	v_fma_f32 v243, -v26, v197, 1.0
	v_fmac_f32_e32 v194, v240, v194
	v_fmac_f32_e32 v195, v241, v195
	v_fmac_f32_e32 v196, v242, v196
	v_fmac_f32_e32 v197, v243, v197
	v_mul_f32_e32 v198, v14, v194
	v_mul_f32_e32 v199, v15, v195
	v_mul_f32_e32 v200, v16, v196
	v_mul_f32_e32 v201, v17, v197
	v_mul_f32_e32 v202, v10, v194
	v_mul_f32_e32 v203, v11, v195
	v_mul_f32_e32 v204, v12, v196
	v_mul_f32_e32 v205, v13, v197
	v_mul_f32_e32 v206, v22, v194
	v_mul_f32_e32 v207, v23, v195
	v_mul_f32_e32 v208, v24, v196
	v_mul_f32_e32 v209, v25, v197
	v_mul_f32_e32 v210, v0, v194
	v_mul_f32_e32 v211, v1, v195
	v_mul_f32_e32 v212, v2, v196
	v_mul_f32_e32 v213, v3, v197
	v_and_b32_e32 v240, 3, v174
	v_mul_u32_u24_e32 v240, 0x87e, v240
	v_mov_b32_e32 v241, 0
	v_lshl_add_u64 v[238:239], v[6:7], 0, v[240:241]
	s_mov_b32 vcc_lo, 0x55555555
	s_mov_b32 vcc_hi, 0x55555555
	s_nop 1
	v_cndmask_b32_dpp v214, v199, v198, vcc quad_perm:[1,0,3,2] row_mask:0xf bank_mask:0xf
	v_cndmask_b32_dpp v216, v201, v200, vcc quad_perm:[1,0,3,2] row_mask:0xf bank_mask:0xf
	v_cndmask_b32_dpp v218, v203, v202, vcc quad_perm:[1,0,3,2] row_mask:0xf bank_mask:0xf
	v_cndmask_b32_dpp v220, v205, v204, vcc quad_perm:[1,0,3,2] row_mask:0xf bank_mask:0xf
	v_cndmask_b32_dpp v222, v207, v206, vcc quad_perm:[1,0,3,2] row_mask:0xf bank_mask:0xf
	v_cndmask_b32_dpp v224, v209, v208, vcc quad_perm:[1,0,3,2] row_mask:0xf bank_mask:0xf
	v_cndmask_b32_dpp v226, v211, v210, vcc quad_perm:[1,0,3,2] row_mask:0xf bank_mask:0xf
	v_cndmask_b32_dpp v228, v213, v212, vcc quad_perm:[1,0,3,2] row_mask:0xf bank_mask:0xf
	s_mov_b32 vcc_lo, 0xaaaaaaaa
	s_mov_b32 vcc_hi, 0xaaaaaaaa
	s_nop 1
	v_cndmask_b32_dpp v215, v198, v199, vcc quad_perm:[1,0,3,2] row_mask:0xf bank_mask:0xf
	v_cndmask_b32_dpp v217, v200, v201, vcc quad_perm:[1,0,3,2] row_mask:0xf bank_mask:0xf
	v_cndmask_b32_dpp v219, v202, v203, vcc quad_perm:[1,0,3,2] row_mask:0xf bank_mask:0xf
	v_cndmask_b32_dpp v221, v204, v205, vcc quad_perm:[1,0,3,2] row_mask:0xf bank_mask:0xf
	v_cndmask_b32_dpp v223, v206, v207, vcc quad_perm:[1,0,3,2] row_mask:0xf bank_mask:0xf
	v_cndmask_b32_dpp v225, v208, v209, vcc quad_perm:[1,0,3,2] row_mask:0xf bank_mask:0xf
	v_cndmask_b32_dpp v227, v210, v211, vcc quad_perm:[1,0,3,2] row_mask:0xf bank_mask:0xf
	v_cndmask_b32_dpp v229, v212, v213, vcc quad_perm:[1,0,3,2] row_mask:0xf bank_mask:0xf
	s_mov_b32 vcc_lo, 0x33333333
	s_mov_b32 vcc_hi, 0x33333333
	s_nop 1
	v_cndmask_b32_dpp v198, v216, v214, vcc quad_perm:[2,3,0,1] row_mask:0xf bank_mask:0xf
	v_cndmask_b32_dpp v199, v217, v215, vcc quad_perm:[2,3,0,1] row_mask:0xf bank_mask:0xf
	v_cndmask_b32_dpp v202, v220, v218, vcc quad_perm:[2,3,0,1] row_mask:0xf bank_mask:0xf
	v_cndmask_b32_dpp v203, v221, v219, vcc quad_perm:[2,3,0,1] row_mask:0xf bank_mask:0xf
	v_cndmask_b32_dpp v206, v224, v222, vcc quad_perm:[2,3,0,1] row_mask:0xf bank_mask:0xf
	v_cndmask_b32_dpp v207, v225, v223, vcc quad_perm:[2,3,0,1] row_mask:0xf bank_mask:0xf
	v_cndmask_b32_dpp v210, v228, v226, vcc quad_perm:[2,3,0,1] row_mask:0xf bank_mask:0xf
	v_cndmask_b32_dpp v211, v229, v227, vcc quad_perm:[2,3,0,1] row_mask:0xf bank_mask:0xf
	s_mov_b32 vcc_lo, 0xcccccccc
	s_mov_b32 vcc_hi, 0xcccccccc
	s_nop 1
	v_cndmask_b32_dpp v200, v214, v216, vcc quad_perm:[2,3,0,1] row_mask:0xf bank_mask:0xf
	v_cndmask_b32_dpp v201, v215, v217, vcc quad_perm:[2,3,0,1] row_mask:0xf bank_mask:0xf
	v_cndmask_b32_dpp v204, v218, v220, vcc quad_perm:[2,3,0,1] row_mask:0xf bank_mask:0xf
	v_cndmask_b32_dpp v205, v219, v221, vcc quad_perm:[2,3,0,1] row_mask:0xf bank_mask:0xf
	v_cndmask_b32_dpp v208, v222, v224, vcc quad_perm:[2,3,0,1] row_mask:0xf bank_mask:0xf
	v_cndmask_b32_dpp v209, v223, v225, vcc quad_perm:[2,3,0,1] row_mask:0xf bank_mask:0xf
	v_cndmask_b32_dpp v212, v226, v228, vcc quad_perm:[2,3,0,1] row_mask:0xf bank_mask:0xf
	v_cndmask_b32_dpp v213, v227, v229, vcc quad_perm:[2,3,0,1] row_mask:0xf bank_mask:0xf
	v_cvt_pk_bf16_f32 v230, v198, v199
	v_cvt_pk_bf16_f32 v231, v200, v201
	v_cvt_pk_bf16_f32 v232, v202, v203
	v_cvt_pk_bf16_f32 v233, v204, v205
	v_cvt_pk_bf16_f32 v234, v206, v207
	v_cvt_pk_bf16_f32 v235, v208, v209
	v_cvt_pk_bf16_f32 v236, v210, v211
	v_cvt_pk_bf16_f32 v237, v212, v213
	global_store_dwordx2 v[238:239], v[230:231], off offset:0
	global_store_dwordx2 v[238:239], v[232:233], off offset:32
	global_store_dwordx2 v[238:239], v[234:235], off offset:64
	global_store_dwordx2 v[238:239], v[236:237], off offset:96
	s_cbranch_scc1 .LBB0_2671
